# nt hint also on the f32 row stores (x1, y) of phases I and L
# speedup vs baseline: 1.0012x; 1.0012x over previous
.LBB0_1512:
	v_add_co_u32_e32 v4, vcc, 0xfffff000, v70
	v_mov_b32_e32 v77, v137
	s_nop 0
	v_addc_co_u32_e32 v5, vcc, -1, v71, vcc
	v_add_co_u32_e32 v80, vcc, 0xffffd000, v68
	global_load_dwordx2 v[118:119], v[4:5], off offset:-3584 nt
	s_nop 0
	v_addc_co_u32_e32 v81, vcc, -1, v69, vcc
	global_load_dwordx4 v[48:51], v[80:81], off offset:-3072 nt
	global_load_dwordx2 v[110:111], v[4:5], off offset:-3072 nt
	global_load_dwordx4 v[32:35], v[80:81], off offset:-2048 nt
	global_load_dwordx2 v[112:113], v[4:5], off offset:-2560 nt
	global_load_dwordx4 v[16:19], v[80:81], off offset:-1024 nt
	global_load_dwordx2 v[0:1], v[4:5], off offset:-2048 nt
	v_add_co_u32_e32 v82, vcc, s80, v68
	v_mov_b32_e32 v79, v137
	s_nop 0
	v_addc_co_u32_e32 v83, vcc, -1, v69, vcc
	v_add_co_u32_e32 v108, vcc, s33, v68
	s_movk_i32 s2, 0x3fff
	s_nop 0
	v_addc_co_u32_e32 v109, vcc, -1, v69, vcc
	s_waitcnt vmcnt(4)
	v_and_b32_e32 v121, 0xffff0000, v111
	v_and_b32_e32 v149, 0xffff0000, v119
	v_and_b32_e32 v147, 0xffff0000, v118
	v_lshlrev_b32_e32 v148, 16, v119
	s_waitcnt vmcnt(0)
	v_lshlrev_b32_e32 v89, 16, v0
	v_and_b32_e32 v87, 0xffff0000, v0
	v_lshlrev_b32_e32 v84, 16, v1
	v_and_b32_e32 v85, 0xffff0000, v1
	global_load_dwordx4 v[0:3], v[80:81], off nt
	global_load_dwordx2 v[122:123], v[4:5], off offset:-1536 nt
	global_load_dwordx4 v[52:55], v[82:83], off offset:-3072 nt
	global_load_dwordx2 v[114:115], v[4:5], off offset:-1024 nt
	global_load_dwordx4 v[36:39], v[82:83], off offset:-2048 nt
	global_load_dwordx2 v[116:117], v[4:5], off offset:-512 nt
	global_load_dwordx4 v[20:23], v[82:83], off offset:-1024 nt
	s_nop 0
	global_load_dwordx2 v[4:5], v[70:71], off offset:-4096 nt
	v_mul_f32_e32 v86, v149, v149
	v_lshlrev_b32_e32 v146, 16, v118
	v_pk_fma_f32 v[124:125], v[148:149], v[148:149], v[86:87] op_sel_hi:[1,1,0]
	v_and_b32_e32 v120, 0xffff0000, v110
	v_mul_f32_e32 v86, v147, v147
	v_lshlrev_b32_e32 v119, 16, v111
	v_lshlrev_b32_e32 v118, 16, v110
	v_pk_mul_f32 v[110:111], v[120:121], v[120:121]
	v_pk_fma_f32 v[138:139], v[146:147], v[146:147], v[86:87] op_sel_hi:[1,1,0]
	v_pk_fma_f32 v[134:135], v[118:119], v[118:119], v[110:111]
	v_mov_b32_e32 v88, v138
	v_mov_b32_e32 v144, v124
	v_mov_b32_e32 v145, v89
	v_and_b32_e32 v111, 0xffff0000, v112
	v_mul_f32_e32 v65, v87, v87
	v_pk_add_f32 v[124:125], v[138:139], v[124:125]
	v_pk_mul_f32 v[138:139], v[88:89], v[144:145]
	v_pk_add_f32 v[134:135], v[134:135], v[134:135] op_sel:[0,1] op_sel_hi:[1,0]
	v_lshlrev_b32_e32 v110, 16, v112
	v_lshlrev_b32_e32 v112, 16, v113
	v_and_b32_e32 v113, 0xffff0000, v113
	v_mov_b32_e32 v125, v139
	v_mov_b32_e32 v135, v65
	v_mul_f32_e32 v86, v111, v111
	v_pk_add_f32 v[124:125], v[124:125], v[134:135]
	v_pk_fma_f32 v[134:135], v[110:111], v[110:111], v[86:87] op_sel_hi:[1,1,0]
	v_mul_f32_e32 v86, v113, v113
	v_mul_f32_e32 v73, v84, v84
	v_mul_f32_e32 v75, v85, v85
	v_pk_fma_f32 v[138:139], v[112:113], v[112:113], v[86:87] op_sel_hi:[1,1,0]
	v_mov_b32_e32 v135, v73
	v_mov_b32_e32 v139, v75
	v_pk_add_f32 v[134:135], v[134:135], v[138:139]
	s_waitcnt vmcnt(6)
	v_and_b32_e32 v153, 0xffff0000, v123
	s_waitcnt vmcnt(0)
	v_lshlrev_b32_e32 v95, 16, v4
	v_and_b32_e32 v93, 0xffff0000, v4
	v_lshlrev_b32_e32 v90, 16, v5
	v_and_b32_e32 v91, 0xffff0000, v5
	global_load_dwordx4 v[4:7], v[82:83], off nt
	global_load_dwordx2 v[130:131], v[70:71], off offset:-3584 nt
	global_load_dwordx4 v[56:59], v[108:109], off offset:-3072 nt
	global_load_dwordx2 v[126:127], v[70:71], off offset:-3072 nt
	global_load_dwordx4 v[40:43], v[108:109], off offset:-2048 nt
	global_load_dwordx2 v[128:129], v[70:71], off offset:-2560 nt
	global_load_dwordx4 v[24:27], v[108:109], off offset:-1024 nt
	global_load_dwordx2 v[8:9], v[70:71], off offset:-2048 nt
	v_and_b32_e32 v151, 0xffff0000, v122
	v_lshlrev_b32_e32 v152, 16, v123
	v_mul_f32_e32 v86, v153, v153
	v_pk_add_f32 v[134:135], v[124:125], v[134:135]
	v_lshlrev_b32_e32 v150, 16, v122
	v_pk_fma_f32 v[138:139], v[152:153], v[152:153], v[86:87] op_sel_hi:[1,1,0]
	v_and_b32_e32 v125, 0xffff0000, v115
	v_and_b32_e32 v124, 0xffff0000, v114
	v_mul_f32_e32 v86, v151, v151
	v_lshlrev_b32_e32 v123, 16, v115
	v_lshlrev_b32_e32 v122, 16, v114
	v_pk_mul_f32 v[114:115], v[124:125], v[124:125]
	v_pk_fma_f32 v[154:155], v[150:151], v[150:151], v[86:87] op_sel_hi:[1,1,0]
	v_pk_fma_f32 v[144:145], v[122:123], v[122:123], v[114:115]
	v_mov_b32_e32 v94, v154
	v_mov_b32_e32 v156, v138
	v_mov_b32_e32 v157, v95
	v_and_b32_e32 v115, 0xffff0000, v116
	v_mul_f32_e32 v65, v93, v93
	v_pk_add_f32 v[138:139], v[154:155], v[138:139]
	v_pk_mul_f32 v[154:155], v[94:95], v[156:157]
	v_pk_add_f32 v[144:145], v[144:145], v[144:145] op_sel:[0,1] op_sel_hi:[1,0]
	v_lshlrev_b32_e32 v114, 16, v116
	v_lshlrev_b32_e32 v116, 16, v117
	v_and_b32_e32 v117, 0xffff0000, v117
	v_mov_b32_e32 v139, v155
	v_mov_b32_e32 v145, v65
	v_mul_f32_e32 v86, v115, v115
	v_pk_add_f32 v[138:139], v[138:139], v[144:145]
	v_pk_fma_f32 v[144:145], v[114:115], v[114:115], v[86:87] op_sel_hi:[1,1,0]
	v_mul_f32_e32 v86, v117, v117
	v_mul_f32_e32 v73, v90, v90
	v_mul_f32_e32 v75, v91, v91
	v_pk_fma_f32 v[154:155], v[116:117], v[116:117], v[86:87] op_sel_hi:[1,1,0]
	v_mov_b32_e32 v145, v73
	v_mov_b32_e32 v155, v75
	v_pk_add_f32 v[144:145], v[144:145], v[154:155]
	s_waitcnt vmcnt(6)
	v_and_b32_e32 v157, 0xffff0000, v131
	s_waitcnt vmcnt(0)
	v_lshlrev_b32_e32 v101, 16, v8
	v_and_b32_e32 v99, 0xffff0000, v8
	v_lshlrev_b32_e32 v96, 16, v9
	v_and_b32_e32 v97, 0xffff0000, v9
	global_load_dwordx4 v[8:11], v[68:69], off offset:-4096 nt
	global_load_dwordx2 v[140:141], v[70:71], off offset:-1536 nt
	global_load_dwordx4 v[60:63], v[68:69], off offset:-3072 nt
	global_load_dwordx2 v[142:143], v[70:71], off offset:-1024 nt
	global_load_dwordx4 v[44:47], v[68:69], off offset:-2048 nt
	global_load_dwordx2 v[132:133], v[70:71], off offset:-512 nt
	global_load_dwordx4 v[28:31], v[68:69], off offset:-1024 nt
	global_load_dwordx2 v[12:13], v[70:71], off nt
	v_pk_add_f32 v[138:139], v[138:139], v[144:145]
	v_mov_b32_e32 v145, v134
	v_mov_b32_e32 v144, v138
	v_mov_b32_e32 v134, v139
	v_pk_add_f32 v[134:135], v[144:145], v[134:135]
	ds_bpermute_b32 v139, v162, v135
	ds_bpermute_b32 v138, v162, v134
	v_mov_b64_e32 v[144:145], s[90:91]
	v_and_b32_e32 v155, 0xffff0000, v130
	v_lshlrev_b32_e32 v156, 16, v131
	v_mul_f32_e32 v86, v157, v157
	s_waitcnt lgkmcnt(0)
	v_pk_add_f32 v[134:135], v[134:135], v[138:139]
	ds_bpermute_b32 v139, v163, v135
	ds_bpermute_b32 v138, v163, v134
	v_lshlrev_b32_e32 v154, 16, v130
	v_pk_fma_f32 v[130:131], v[156:157], v[156:157], v[86:87] op_sel_hi:[1,1,0]
	v_mul_f32_e32 v86, v155, v155
	v_pk_fma_f32 v[160:161], v[154:155], v[154:155], v[86:87] op_sel_hi:[1,1,0]
	s_waitcnt lgkmcnt(0)
	v_pk_add_f32 v[134:135], v[134:135], v[138:139]
	ds_bpermute_b32 v139, v164, v135
	ds_bpermute_b32 v138, v164, v134
	v_mov_b32_e32 v100, v160
	v_mov_b32_e32 v168, v130
	v_mov_b32_e32 v169, v101
	v_pk_add_f32 v[130:131], v[160:161], v[130:131]
	s_waitcnt lgkmcnt(0)
	v_pk_add_f32 v[134:135], v[134:135], v[138:139]
	ds_bpermute_b32 v139, v165, v135
	ds_bpermute_b32 v138, v165, v134
	v_pk_mul_f32 v[160:161], v[100:101], v[168:169]
	v_mul_f32_e32 v75, v97, v97
	v_mov_b32_e32 v131, v161
	v_mov_b32_e32 v98, v101
	s_waitcnt lgkmcnt(0)
	v_pk_add_f32 v[134:135], v[134:135], v[138:139]
	ds_bpermute_b32 v139, v166, v135
	ds_bpermute_b32 v138, v166, v134
	v_lshl_add_u64 v[70:71], v[70:71], 0, s[76:77]
	s_waitcnt lgkmcnt(0)
	v_pk_add_f32 v[134:135], v[134:135], v[138:139]
	ds_bpermute_b32 v139, v167, v135
	ds_bpermute_b32 v138, v167, v134
	s_waitcnt lgkmcnt(0)
	v_pk_add_f32 v[134:135], v[134:135], v[138:139]
	s_nop 0
	v_pk_fma_f32 v[134:135], v[134:135], s[82:83], v[144:145] op_sel_hi:[1,0,0]
	v_and_b32_e32 v139, 0xffff0000, v127
	v_mul_f32_e32 v65, 0x4b800000, v135
	v_cmp_gt_f32_e64 s[4:5], s81, v135
	v_cmp_gt_f32_e32 vcc, s81, v134
	v_and_b32_e32 v138, 0xffff0000, v126
	v_cndmask_b32_e64 v65, v135, v65, s[4:5]
	v_rsq_f32_e32 v65, v65
	v_lshlrev_b32_e32 v135, 16, v127
	v_mul_f32_e32 v73, 0x45800000, v65
	v_cndmask_b32_e64 v92, v65, v73, s[4:5]
	v_mul_f32_e32 v65, 0x4b800000, v134
	v_cndmask_b32_e32 v65, v134, v65, vcc
	v_rsq_f32_e32 v65, v65
	v_lshlrev_b32_e32 v134, 16, v126
	v_pk_mul_f32 v[126:127], v[138:139], v[138:139]
	v_pk_mul_f32 v[148:149], v[92:93], v[148:149] op_sel_hi:[0,1]
	v_mul_f32_e32 v73, 0x45800000, v65
	v_pk_fma_f32 v[158:159], v[134:135], v[134:135], v[126:127]
	v_cndmask_b32_e32 v88, v65, v73, vcc
	v_and_b32_e32 v127, 0xffff0000, v128
	v_mul_f32_e32 v65, v99, v99
	v_pk_add_f32 v[158:159], v[158:159], v[158:159] op_sel:[0,1] op_sel_hi:[1,0]
	v_lshlrev_b32_e32 v126, 16, v128
	v_lshlrev_b32_e32 v128, 16, v129
	v_and_b32_e32 v129, 0xffff0000, v129
	v_mov_b32_e32 v159, v65
	v_mul_f32_e32 v86, v127, v127
	v_pk_add_f32 v[130:131], v[130:131], v[158:159]
	v_pk_fma_f32 v[158:159], v[126:127], v[126:127], v[86:87] op_sel_hi:[1,1,0]
	v_mul_f32_e32 v86, v129, v129
	v_mul_f32_e32 v73, v96, v96
	v_pk_fma_f32 v[160:161], v[128:129], v[128:129], v[86:87] op_sel_hi:[1,1,0]
	v_mov_b32_e32 v159, v73
	v_mov_b32_e32 v161, v75
	v_pk_add_f32 v[158:159], v[158:159], v[160:161]
	s_waitcnt vmcnt(6)
	v_and_b32_e32 v161, 0xffff0000, v141
	v_pk_add_f32 v[168:169], v[130:131], v[158:159]
	v_and_b32_e32 v159, 0xffff0000, v140
	v_lshlrev_b32_e32 v160, 16, v141
	v_mul_f32_e32 v86, v161, v161
	v_lshlrev_b32_e32 v158, 16, v140
	v_pk_fma_f32 v[170:171], v[160:161], v[160:161], v[86:87] op_sel_hi:[1,1,0]
	s_waitcnt vmcnt(4)
	v_lshlrev_b32_e32 v141, 16, v143
	v_lshlrev_b32_e32 v140, 16, v142
	v_and_b32_e32 v143, 0xffff0000, v143
	v_and_b32_e32 v142, 0xffff0000, v142
	v_mul_f32_e32 v86, v159, v159
	s_waitcnt vmcnt(0)
	v_lshlrev_b32_e32 v107, 16, v12
	v_pk_mul_f32 v[130:131], v[142:143], v[142:143]
	v_pk_fma_f32 v[188:189], v[158:159], v[158:159], v[86:87] op_sel_hi:[1,1,0]
	v_and_b32_e32 v105, 0xffff0000, v12
	v_pk_fma_f32 v[172:173], v[140:141], v[140:141], v[130:131]
	v_mov_b32_e32 v106, v188
	v_mov_b32_e32 v190, v170
	v_mov_b32_e32 v191, v107
	v_and_b32_e32 v131, 0xffff0000, v132
	v_mul_f32_e32 v65, v105, v105
	v_pk_add_f32 v[170:171], v[188:189], v[170:171]
	v_pk_mul_f32 v[188:189], v[106:107], v[190:191]
	v_pk_add_f32 v[172:173], v[172:173], v[172:173] op_sel:[0,1] op_sel_hi:[1,0]
	v_lshlrev_b32_e32 v130, 16, v132
	v_lshlrev_b32_e32 v132, 16, v133
	v_and_b32_e32 v133, 0xffff0000, v133
	v_mov_b32_e32 v171, v189
	v_mov_b32_e32 v173, v65
	v_mul_f32_e32 v86, v131, v131
	v_lshlrev_b32_e32 v102, 16, v13
	v_and_b32_e32 v103, 0xffff0000, v13
	v_pk_add_f32 v[170:171], v[170:171], v[172:173]
	v_pk_fma_f32 v[172:173], v[130:131], v[130:131], v[86:87] op_sel_hi:[1,1,0]
	v_mul_f32_e32 v86, v133, v133
	v_mul_f32_e32 v73, v102, v102
	v_mul_f32_e32 v75, v103, v103
	v_pk_fma_f32 v[188:189], v[132:133], v[132:133], v[86:87] op_sel_hi:[1,1,0]
	v_mov_b32_e32 v173, v73
	v_mov_b32_e32 v189, v75
	v_pk_add_f32 v[172:173], v[172:173], v[188:189]
	v_pk_mul_f32 v[146:147], v[92:93], v[146:147] op_sel_hi:[0,1]
	v_pk_add_f32 v[170:171], v[170:171], v[172:173]
	v_mov_b32_e32 v173, v168
	v_mov_b32_e32 v172, v170
	v_mov_b32_e32 v168, v171
	v_pk_add_f32 v[168:169], v[172:173], v[168:169]
	ds_bpermute_b32 v171, v162, v169
	ds_bpermute_b32 v170, v162, v168
	v_mov_b32_e32 v75, v137
	global_load_dwordx4 v[12:15], v[68:69], off nt
	v_mov_b32_e32 v86, v89
	v_mov_b32_e32 v104, v107
	s_waitcnt lgkmcnt(0)
	v_pk_add_f32 v[168:169], v[168:169], v[170:171]
	ds_bpermute_b32 v171, v163, v169
	ds_bpermute_b32 v170, v163, v168
	s_waitcnt lgkmcnt(0)
	v_pk_add_f32 v[168:169], v[168:169], v[170:171]
	ds_bpermute_b32 v171, v164, v169
	ds_bpermute_b32 v170, v164, v168
	s_waitcnt lgkmcnt(0)
	v_pk_add_f32 v[168:169], v[168:169], v[170:171]
	ds_bpermute_b32 v171, v165, v169
	ds_bpermute_b32 v170, v165, v168
	s_waitcnt lgkmcnt(0)
	v_pk_add_f32 v[168:169], v[168:169], v[170:171]
	ds_bpermute_b32 v171, v166, v169
	ds_bpermute_b32 v170, v166, v168
	s_waitcnt lgkmcnt(0)
	v_pk_add_f32 v[168:169], v[168:169], v[170:171]
	ds_bpermute_b32 v171, v167, v169
	ds_bpermute_b32 v170, v167, v168
	s_waitcnt lgkmcnt(0)
	v_pk_add_f32 v[168:169], v[168:169], v[170:171]
	s_nop 0
	v_pk_fma_f32 v[144:145], v[168:169], s[82:83], v[144:145] op_sel_hi:[1,0,0]
	global_load_dwordx4 v[168:171], v[66:67], off
	v_mul_f32_e32 v65, 0x4b800000, v145
	v_cmp_gt_f32_e64 s[4:5], s81, v145
	v_cmp_gt_f32_e32 vcc, s81, v144
	s_waitcnt vmcnt(0)
	v_pk_mul_f32 v[146:147], v[146:147], v[168:169]
	v_cndmask_b32_e64 v65, v145, v65, s[4:5]
	v_rsq_f32_e32 v65, v65
	v_pk_mul_f32 v[148:149], v[148:149], v[170:171]
	v_mul_f32_e32 v73, 0x45800000, v65
	v_cndmask_b32_e64 v100, v65, v73, s[4:5]
	v_mul_f32_e32 v65, 0x4b800000, v144
	v_cndmask_b32_e32 v65, v144, v65, vcc
	v_rsq_f32_e32 v65, v65
	s_nop 0
	v_mul_f32_e32 v73, 0x45800000, v65
	v_cndmask_b32_e32 v94, v65, v73, vcc
	v_add_u32_e32 v65, 0xffffe000, v64
	v_lshrrev_b32_e32 v65, 12, v65
	v_mad_u32_u24 v65, v65, s83, s83
	v_cmp_lt_i32_e32 vcc, s60, v64
	v_mov_b32_e32 v73, v137
	v_add_u32_e32 v64, s68, v64
	v_cndmask_b32_e32 v136, 0, v65, vcc
	v_lshl_add_u64 v[144:145], v[136:137], 2, s[84:85]
	v_lshl_add_u64 v[144:145], v[144:145], 0, s[62:63]
	v_lshl_add_u64 v[172:173], v[144:145], 0, v[72:73]
	global_load_dwordx4 v[188:191], v[172:173], off
	v_cmp_lt_i32_e32 vcc, s2, v64
	s_or_b64 s[8:9], vcc, s[8:9]
	s_waitcnt vmcnt(0)
	v_pk_fma_f32 v[50:51], v[190:191], v[148:149], v[50:51]
	v_pk_fma_f32 v[48:49], v[188:189], v[146:147], v[48:49]
	global_store_dwordx4 v[80:81], v[48:51], off offset:-3072 nt
	s_nop 1
	v_pk_mul_f32 v[48:49], v[88:89], v[152:153] op_sel_hi:[0,1]
	v_pk_mul_f32 v[50:51], v[88:89], v[150:151] op_sel_hi:[0,1]
	v_pk_mul_f32 v[146:147], v[50:51], v[168:169]
	v_pk_mul_f32 v[48:49], v[48:49], v[170:171]
	s_nop 0
	v_pk_fma_f32 v[50:51], v[190:191], v[48:49], v[54:55]
	v_pk_fma_f32 v[48:49], v[188:189], v[146:147], v[52:53]
	global_store_dwordx4 v[82:83], v[48:51], off offset:-3072 nt
	s_nop 1
	v_pk_mul_f32 v[48:49], v[100:101], v[156:157] op_sel_hi:[0,1]
	v_pk_mul_f32 v[50:51], v[100:101], v[154:155] op_sel_hi:[0,1]
	v_pk_mul_f32 v[52:53], v[168:169], v[50:51]
	v_pk_mul_f32 v[48:49], v[170:171], v[48:49]
	s_nop 0
	v_pk_fma_f32 v[50:51], v[190:191], v[48:49], v[58:59]
	v_pk_fma_f32 v[48:49], v[188:189], v[52:53], v[56:57]
	global_store_dwordx4 v[108:109], v[48:51], off offset:-3072 nt
	v_mov_b32_e32 v56, v118
	v_mov_b32_e32 v57, v120
	v_pk_mul_f32 v[48:49], v[94:95], v[160:161] op_sel_hi:[0,1]
	v_pk_mul_f32 v[50:51], v[94:95], v[158:159] op_sel_hi:[0,1]
	v_pk_mul_f32 v[52:53], v[168:169], v[50:51]
	v_pk_mul_f32 v[48:49], v[170:171], v[48:49]
	v_mov_b32_e32 v120, v119
	v_pk_fma_f32 v[50:51], v[190:191], v[48:49], v[62:63]
	v_pk_fma_f32 v[48:49], v[188:189], v[52:53], v[60:61]
	global_store_dwordx4 v[68:69], v[48:51], off offset:-3072 nt
	global_load_dwordx4 v[48:51], v[66:67], off offset:1024
	v_lshl_add_u64 v[52:53], v[144:145], 0, v[74:75]
	global_load_dwordx4 v[52:55], v[52:53], off
	v_pk_mul_f32 v[56:57], v[92:93], v[56:57] op_sel_hi:[0,1]
	v_pk_mul_f32 v[58:59], v[92:93], v[120:121] op_sel_hi:[0,1]
	s_waitcnt vmcnt(1)
	v_pk_mul_f32 v[58:59], v[58:59], v[50:51]
	v_pk_mul_f32 v[56:57], v[56:57], v[48:49]
	s_waitcnt vmcnt(0)
	v_pk_fma_f32 v[34:35], v[54:55], v[58:59], v[34:35]
	v_pk_fma_f32 v[32:33], v[52:53], v[56:57], v[32:33]
	global_store_dwordx4 v[80:81], v[32:35], off offset:-2048 nt
	s_nop 1
	v_mov_b32_e32 v32, v122
	v_mov_b32_e32 v33, v124
	v_mov_b32_e32 v124, v123
	v_pk_mul_f32 v[32:33], v[88:89], v[32:33] op_sel_hi:[0,1]
	v_pk_mul_f32 v[34:35], v[88:89], v[124:125] op_sel_hi:[0,1]
	v_pk_mul_f32 v[34:35], v[34:35], v[50:51]
	v_pk_mul_f32 v[32:33], v[32:33], v[48:49]
	v_pk_fma_f32 v[34:35], v[54:55], v[34:35], v[38:39]
	v_pk_fma_f32 v[32:33], v[52:53], v[32:33], v[36:37]
	global_store_dwordx4 v[82:83], v[32:35], off offset:-2048 nt
	v_lshl_add_u64 v[36:37], v[144:145], 0, v[76:77]
	s_nop 0
	v_mov_b32_e32 v32, v134
	v_mov_b32_e32 v33, v138
	v_mov_b32_e32 v138, v135
	v_pk_mul_f32 v[32:33], v[100:101], v[32:33] op_sel_hi:[0,1]
	v_pk_mul_f32 v[34:35], v[100:101], v[138:139] op_sel_hi:[0,1]
	v_pk_mul_f32 v[34:35], v[34:35], v[50:51]
	v_pk_mul_f32 v[32:33], v[32:33], v[48:49]
	v_pk_fma_f32 v[34:35], v[54:55], v[34:35], v[42:43]
	v_pk_fma_f32 v[32:33], v[52:53], v[32:33], v[40:41]
	global_store_dwordx4 v[108:109], v[32:35], off offset:-2048 nt
	v_pk_mul_f32 v[40:41], v[92:93], v[110:111] op_sel_hi:[0,1]
	v_pk_mul_f32 v[42:43], v[92:93], v[112:113] op_sel_hi:[0,1]
	v_mov_b32_e32 v32, v140
	v_mov_b32_e32 v33, v142
	v_mov_b32_e32 v142, v141
	v_pk_mul_f32 v[32:33], v[94:95], v[32:33] op_sel_hi:[0,1]
	v_pk_mul_f32 v[34:35], v[94:95], v[142:143] op_sel_hi:[0,1]
	v_pk_mul_f32 v[34:35], v[50:51], v[34:35]
	v_pk_mul_f32 v[32:33], v[48:49], v[32:33]
	v_pk_fma_f32 v[34:35], v[54:55], v[34:35], v[46:47]
	v_pk_fma_f32 v[32:33], v[52:53], v[32:33], v[44:45]
	global_store_dwordx4 v[68:69], v[32:35], off offset:-2048 nt
	global_load_dwordx4 v[32:35], v[66:67], off offset:2048
	s_waitcnt vmcnt(0)
	v_pk_mul_f32 v[42:43], v[42:43], v[34:35]
	global_load_dwordx4 v[36:39], v[36:37], off
	v_pk_mul_f32 v[40:41], v[40:41], v[32:33]
	s_waitcnt vmcnt(0)
	v_pk_fma_f32 v[18:19], v[38:39], v[42:43], v[18:19]
	v_pk_fma_f32 v[16:17], v[36:37], v[40:41], v[16:17]
	global_store_dwordx4 v[80:81], v[16:19], off offset:-1024 nt
	s_nop 1
	v_pk_mul_f32 v[16:17], v[88:89], v[114:115] op_sel_hi:[0,1]
	v_pk_mul_f32 v[18:19], v[88:89], v[116:117] op_sel_hi:[0,1]
	v_pk_mul_f32 v[18:19], v[18:19], v[34:35]
	v_pk_mul_f32 v[16:17], v[16:17], v[32:33]
	v_pk_fma_f32 v[18:19], v[38:39], v[18:19], v[22:23]
	v_pk_fma_f32 v[16:17], v[36:37], v[16:17], v[20:21]
	global_store_dwordx4 v[82:83], v[16:19], off offset:-1024 nt
	v_lshl_add_u64 v[20:21], v[144:145], 0, v[78:79]
	s_nop 0
	v_pk_mul_f32 v[16:17], v[100:101], v[126:127] op_sel_hi:[0,1]
	v_pk_mul_f32 v[18:19], v[100:101], v[128:129] op_sel_hi:[0,1]
	v_pk_mul_f32 v[18:19], v[18:19], v[34:35]
	v_pk_mul_f32 v[16:17], v[16:17], v[32:33]
	v_pk_fma_f32 v[18:19], v[38:39], v[18:19], v[26:27]
	v_pk_fma_f32 v[16:17], v[36:37], v[16:17], v[24:25]
	global_store_dwordx4 v[108:109], v[16:19], off offset:-1024 nt
	v_pk_mul_f32 v[24:25], v[92:93], v[86:87] op_sel_hi:[0,1]
	v_pk_mul_f32 v[26:27], v[92:93], v[84:85] op_sel_hi:[0,1]
	v_pk_mul_f32 v[16:17], v[94:95], v[130:131] op_sel_hi:[0,1]
	v_pk_mul_f32 v[18:19], v[94:95], v[132:133] op_sel_hi:[0,1]
	v_pk_mul_f32 v[18:19], v[18:19], v[34:35]
	v_pk_mul_f32 v[16:17], v[16:17], v[32:33]
	v_pk_fma_f32 v[18:19], v[38:39], v[18:19], v[30:31]
	v_pk_fma_f32 v[16:17], v[36:37], v[16:17], v[28:29]
	global_store_dwordx4 v[68:69], v[16:19], off offset:-1024 nt
	global_load_dwordx4 v[16:19], v[66:67], off offset:3072
	v_mov_b32_e32 v92, v95
	global_load_dwordx4 v[20:23], v[20:21], off
	s_waitcnt vmcnt(1)
	v_pk_mul_f32 v[26:27], v[26:27], v[18:19]
	v_pk_mul_f32 v[24:25], v[24:25], v[16:17]
	s_waitcnt vmcnt(0)
	v_pk_fma_f32 v[2:3], v[22:23], v[26:27], v[2:3]
	v_pk_fma_f32 v[0:1], v[20:21], v[24:25], v[0:1]
	global_store_dwordx4 v[80:81], v[0:3], off nt
	s_nop 1
	v_pk_mul_f32 v[0:1], v[88:89], v[92:93] op_sel_hi:[0,1]
	v_pk_mul_f32 v[2:3], v[88:89], v[90:91] op_sel_hi:[0,1]
	v_pk_mul_f32 v[2:3], v[2:3], v[18:19]
	v_pk_mul_f32 v[0:1], v[0:1], v[16:17]
	v_pk_fma_f32 v[2:3], v[22:23], v[2:3], v[6:7]
	v_pk_fma_f32 v[0:1], v[20:21], v[0:1], v[4:5]
	global_store_dwordx4 v[82:83], v[0:3], off nt
	s_nop 1
	v_pk_mul_f32 v[0:1], v[100:101], v[98:99] op_sel_hi:[0,1]
	v_pk_mul_f32 v[2:3], v[100:101], v[96:97] op_sel_hi:[0,1]
	v_pk_mul_f32 v[2:3], v[2:3], v[18:19]
	v_pk_mul_f32 v[0:1], v[0:1], v[16:17]
	v_pk_fma_f32 v[2:3], v[22:23], v[2:3], v[10:11]
	v_pk_fma_f32 v[0:1], v[20:21], v[0:1], v[8:9]
	global_store_dwordx4 v[68:69], v[0:3], off offset:-4096 nt
	s_nop 1
	v_pk_mul_f32 v[0:1], v[94:95], v[104:105] op_sel_hi:[0,1]
	v_pk_mul_f32 v[2:3], v[94:95], v[102:103] op_sel_hi:[0,1]
	v_pk_mul_f32 v[2:3], v[2:3], v[18:19]
	v_pk_mul_f32 v[0:1], v[0:1], v[16:17]
	v_pk_fma_f32 v[2:3], v[22:23], v[2:3], v[14:15]
	v_pk_fma_f32 v[0:1], v[20:21], v[0:1], v[12:13]
	global_store_dwordx4 v[68:69], v[0:3], off nt
	v_lshl_add_u64 v[68:69], v[68:69], 0, s[72:73]
	s_andn2_b64 exec, exec, s[8:9]
	s_cbranch_execnz .LBB0_1512

.LBB0_1522:
	v_add_co_u32_e32 v4, vcc, 0xfefff000, v70
	s_mov_b32 s2, 0xff000000
	s_nop 0
	v_addc_co_u32_e32 v5, vcc, -1, v71, vcc
	v_add_co_u32_e32 v20, vcc, s33, v70
	global_load_dwordx2 v[6:7], v[4:5], off offset:-3584 nt
	global_load_dwordx4 v[48:51], v[72:73], off offset:-3072 nt
	global_load_dwordx2 v[12:13], v[4:5], off offset:-3072 nt
	global_load_dwordx4 v[16:19], v[72:73], off offset:-2048 nt
	global_load_dwordx2 v[14:15], v[4:5], off offset:-2560 nt
	global_load_dwordx4 v[8:11], v[72:73], off offset:-1024 nt
	global_load_dwordx2 v[22:23], v[4:5], off offset:-2048 nt
	global_load_dwordx4 v[0:3], v[72:73], off nt
	v_addc_co_u32_e32 v21, vcc, -1, v71, vcc
	global_load_dwordx2 v[24:25], v[20:21], off offset:-3584 nt
	v_mov_b32_e32 v77, v137
	v_mov_b32_e32 v79, v137
	v_mov_b32_e32 v81, v137
	s_waitcnt vmcnt(8)
	v_lshlrev_b32_e32 v26, 16, v6
	v_and_b32_e32 v27, 0xffff0000, v6
	v_lshlrev_b32_e32 v6, 16, v7
	v_and_b32_e32 v7, 0xffff0000, v7
	s_waitcnt vmcnt(0)
	v_lshlrev_b32_e32 v28, 16, v24
	v_and_b32_e32 v29, 0xffff0000, v24
	v_lshlrev_b32_e32 v24, 16, v25
	v_and_b32_e32 v25, 0xffff0000, v25
	v_pk_add_f32 v[150:151], v[6:7], v[24:25]
	global_load_dwordx2 v[6:7], v[20:21], off offset:-3072 nt
	v_pk_add_f32 v[148:149], v[26:27], v[28:29]
	v_lshlrev_b32_e32 v24, 16, v12
	v_and_b32_e32 v25, 0xffff0000, v12
	v_lshlrev_b32_e32 v12, 16, v13
	v_and_b32_e32 v13, 0xffff0000, v13
	s_waitcnt vmcnt(0)
	v_lshlrev_b32_e32 v26, 16, v6
	v_and_b32_e32 v27, 0xffff0000, v6
	v_lshlrev_b32_e32 v6, 16, v7
	v_and_b32_e32 v7, 0xffff0000, v7
	v_pk_add_f32 v[104:105], v[12:13], v[6:7]
	global_load_dwordx2 v[6:7], v[20:21], off offset:-2560 nt
	v_pk_add_f32 v[102:103], v[24:25], v[26:27]
	v_lshlrev_b32_e32 v12, 16, v14
	v_and_b32_e32 v13, 0xffff0000, v14
	v_mov_b32_e32 v168, v103
	v_mov_b32_e32 v169, v105
	v_pk_mul_f32 v[168:169], v[168:169], v[168:169]
	s_waitcnt vmcnt(0)
	v_lshlrev_b32_e32 v24, 16, v6
	v_and_b32_e32 v25, 0xffff0000, v6
	v_pk_add_f32 v[92:93], v[12:13], v[24:25]
	v_lshlrev_b32_e32 v12, 16, v15
	v_and_b32_e32 v13, 0xffff0000, v15
	v_lshlrev_b32_e32 v6, 16, v7
	v_and_b32_e32 v7, 0xffff0000, v7
	v_pk_add_f32 v[94:95], v[12:13], v[6:7]
	global_load_dwordx2 v[6:7], v[20:21], off offset:-2048 nt
	v_lshlrev_b32_e32 v12, 16, v22
	v_and_b32_e32 v13, 0xffff0000, v22
	v_mul_f32_e32 v136, v93, v93
	s_waitcnt vmcnt(0)
	v_lshlrev_b32_e32 v14, 16, v6
	v_and_b32_e32 v15, 0xffff0000, v6
	v_pk_add_f32 v[82:83], v[12:13], v[14:15]
	v_lshlrev_b32_e32 v12, 16, v23
	v_and_b32_e32 v13, 0xffff0000, v23
	v_lshlrev_b32_e32 v6, 16, v7
	v_and_b32_e32 v7, 0xffff0000, v7
	v_pk_add_f32 v[84:85], v[12:13], v[6:7]
	v_add_u32_e32 v6, 0x4001, v64
	v_ashrrev_i32_e32 v7, 31, v6
	v_lshlrev_b64 v[6:7], 12, v[6:7]
	v_lshl_add_u64 v[86:87], v[68:69], 0, v[6:7]
	global_load_dwordx2 v[22:23], v[4:5], off offset:-1536 nt
	global_load_dwordx4 v[52:55], v[86:87], off nt
	global_load_dwordx2 v[28:29], v[4:5], off offset:-1024 nt
	global_load_dwordx4 v[24:27], v[86:87], off offset:1024 nt
	global_load_dwordx2 v[30:31], v[4:5], off offset:-512 nt
	global_load_dwordx4 v[12:15], v[86:87], off offset:2048 nt
	global_load_dwordx2 v[32:33], v[4:5], off nt
	s_nop 0
	global_load_dwordx4 v[4:7], v[86:87], off offset:3072 nt
	global_load_dwordx2 v[34:35], v[20:21], off offset:-1536 nt
	v_pk_mul_f32 v[172:173], v[82:83], v[82:83]
	v_pk_mul_f32 v[188:189], v[84:85], v[84:85]
	s_waitcnt vmcnt(8)
	v_lshlrev_b32_e32 v36, 16, v22
	v_and_b32_e32 v37, 0xffff0000, v22
	v_lshlrev_b32_e32 v22, 16, v23
	v_and_b32_e32 v23, 0xffff0000, v23
	s_waitcnt vmcnt(0)
	v_lshlrev_b32_e32 v38, 16, v34
	v_and_b32_e32 v39, 0xffff0000, v34
	v_lshlrev_b32_e32 v34, 16, v35
	v_and_b32_e32 v35, 0xffff0000, v35
	v_pk_add_f32 v[154:155], v[22:23], v[34:35]
	global_load_dwordx2 v[22:23], v[20:21], off offset:-1024 nt
	v_pk_add_f32 v[152:153], v[36:37], v[38:39]
	global_load_dwordx2 v[20:21], v[20:21], off offset:-512 nt
	v_lshlrev_b32_e32 v34, 16, v28
	v_and_b32_e32 v35, 0xffff0000, v28
	v_lshlrev_b32_e32 v28, 16, v29
	v_and_b32_e32 v29, 0xffff0000, v29
	s_waitcnt vmcnt(1)
	v_lshlrev_b32_e32 v36, 16, v22
	v_and_b32_e32 v37, 0xffff0000, v22
	v_lshlrev_b32_e32 v22, 16, v23
	v_and_b32_e32 v23, 0xffff0000, v23
	v_pk_add_f32 v[114:115], v[28:29], v[22:23]
	v_lshlrev_b32_e32 v22, 16, v30
	v_and_b32_e32 v23, 0xffff0000, v30
	s_waitcnt vmcnt(0)
	v_lshlrev_b32_e32 v28, 16, v20
	v_and_b32_e32 v29, 0xffff0000, v20
	v_pk_add_f32 v[98:99], v[22:23], v[28:29]
	v_lshlrev_b32_e32 v22, 16, v31
	v_and_b32_e32 v23, 0xffff0000, v31
	v_lshlrev_b32_e32 v20, 16, v21
	v_and_b32_e32 v21, 0xffff0000, v21
	v_pk_add_f32 v[100:101], v[22:23], v[20:21]
	global_load_dwordx2 v[20:21], v[70:71], off offset:-4096 nt
	v_lshlrev_b32_e32 v22, 16, v32
	v_and_b32_e32 v23, 0xffff0000, v32
	v_add_co_u32_e32 v32, vcc, s2, v70
	v_pk_add_f32 v[112:113], v[34:35], v[36:37]
	s_movk_i32 s2, 0xdfff
	s_waitcnt vmcnt(0)
	v_lshlrev_b32_e32 v28, 16, v20
	v_and_b32_e32 v29, 0xffff0000, v20
	v_pk_add_f32 v[88:89], v[22:23], v[28:29]
	v_lshlrev_b32_e32 v22, 16, v33
	v_and_b32_e32 v23, 0xffff0000, v33
	v_lshlrev_b32_e32 v20, 16, v21
	v_and_b32_e32 v21, 0xffff0000, v21
	v_pk_add_f32 v[90:91], v[22:23], v[20:21]
	v_add_u32_e32 v20, 0x4002, v64
	v_ashrrev_i32_e32 v21, 31, v20
	v_lshlrev_b64 v[20:21], 12, v[20:21]
	v_addc_co_u32_e32 v33, vcc, -1, v71, vcc
	v_lshl_add_u64 v[96:97], v[68:69], 0, v[20:21]
	global_load_dwordx2 v[34:35], v[32:33], off offset:-3584 nt
	global_load_dwordx4 v[56:59], v[96:97], off nt
	global_load_dwordx2 v[40:41], v[32:33], off offset:-3072 nt
	global_load_dwordx4 v[36:39], v[96:97], off offset:1024 nt
	global_load_dwordx2 v[42:43], v[32:33], off offset:-2560 nt
	global_load_dwordx4 v[28:31], v[96:97], off offset:2048 nt
	global_load_dwordx2 v[44:45], v[32:33], off offset:-2048 nt
	global_load_dwordx4 v[20:23], v[96:97], off offset:3072 nt
	global_load_dwordx2 v[46:47], v[70:71], off offset:-3584 nt
	v_pk_mul_f32 v[190:191], v[90:91], v[90:91]
	s_waitcnt vmcnt(8)
	v_lshlrev_b32_e32 v60, 16, v34
	v_and_b32_e32 v61, 0xffff0000, v34
	v_lshlrev_b32_e32 v34, 16, v35
	v_and_b32_e32 v35, 0xffff0000, v35
	s_waitcnt vmcnt(0)
	v_lshlrev_b32_e32 v62, 16, v46
	v_and_b32_e32 v63, 0xffff0000, v46
	v_lshlrev_b32_e32 v46, 16, v47
	v_and_b32_e32 v47, 0xffff0000, v47
	v_pk_add_f32 v[158:159], v[34:35], v[46:47]
	global_load_dwordx2 v[34:35], v[70:71], off offset:-3072 nt
	v_pk_add_f32 v[156:157], v[60:61], v[62:63]
	v_lshlrev_b32_e32 v46, 16, v40
	v_and_b32_e32 v47, 0xffff0000, v40
	v_lshlrev_b32_e32 v40, 16, v41
	v_and_b32_e32 v41, 0xffff0000, v41
	s_waitcnt vmcnt(0)
	v_lshlrev_b32_e32 v60, 16, v34
	v_and_b32_e32 v61, 0xffff0000, v34
	v_lshlrev_b32_e32 v34, 16, v35
	v_and_b32_e32 v35, 0xffff0000, v35
	v_pk_add_f32 v[126:127], v[40:41], v[34:35]
	global_load_dwordx2 v[34:35], v[70:71], off offset:-2560 nt
	v_pk_add_f32 v[124:125], v[46:47], v[60:61]
	v_lshlrev_b32_e32 v40, 16, v42
	v_and_b32_e32 v41, 0xffff0000, v42
	s_waitcnt vmcnt(0)
	v_lshlrev_b32_e32 v46, 16, v34
	v_and_b32_e32 v47, 0xffff0000, v34
	v_pk_add_f32 v[116:117], v[40:41], v[46:47]
	v_lshlrev_b32_e32 v40, 16, v43
	v_and_b32_e32 v41, 0xffff0000, v43
	v_lshlrev_b32_e32 v34, 16, v35
	v_and_b32_e32 v35, 0xffff0000, v35
	v_pk_add_f32 v[118:119], v[40:41], v[34:35]
	global_load_dwordx2 v[34:35], v[70:71], off offset:-2048 nt
	v_lshlrev_b32_e32 v40, 16, v44
	v_and_b32_e32 v41, 0xffff0000, v44
	s_waitcnt vmcnt(0)
	v_lshlrev_b32_e32 v42, 16, v34
	v_and_b32_e32 v43, 0xffff0000, v34
	v_pk_add_f32 v[106:107], v[40:41], v[42:43]
	v_lshlrev_b32_e32 v40, 16, v45
	v_and_b32_e32 v41, 0xffff0000, v45
	v_lshlrev_b32_e32 v34, 16, v35
	v_and_b32_e32 v35, 0xffff0000, v35
	v_pk_add_f32 v[108:109], v[40:41], v[34:35]
	v_add_u32_e32 v34, 0x4003, v64
	v_ashrrev_i32_e32 v35, 31, v34
	v_lshlrev_b64 v[34:35], 12, v[34:35]
	v_lshl_add_u64 v[110:111], v[68:69], 0, v[34:35]
	global_load_dwordx2 v[120:121], v[32:33], off offset:-1536 nt
	global_load_dwordx4 v[60:63], v[110:111], off nt
	global_load_dwordx2 v[122:123], v[32:33], off offset:-1024 nt
	global_load_dwordx4 v[44:47], v[110:111], off offset:1024 nt
	global_load_dwordx2 v[130:131], v[32:33], off offset:-512 nt
	global_load_dwordx4 v[40:43], v[110:111], off offset:2048 nt
	global_load_dwordx2 v[138:139], v[32:33], off nt
	s_nop 0
	global_load_dwordx4 v[32:35], v[110:111], off offset:3072 nt
	global_load_dwordx2 v[128:129], v[70:71], off offset:-1536 nt
	v_pk_mul_f32 v[192:193], v[108:109], v[108:109]
	s_waitcnt vmcnt(8)
	v_lshlrev_b32_e32 v132, 16, v120
	v_and_b32_e32 v133, 0xffff0000, v120
	v_lshlrev_b32_e32 v120, 16, v121
	v_and_b32_e32 v121, 0xffff0000, v121
	s_waitcnt vmcnt(0)
	v_lshlrev_b32_e32 v134, 16, v128
	v_and_b32_e32 v135, 0xffff0000, v128
	v_lshlrev_b32_e32 v128, 16, v129
	v_and_b32_e32 v129, 0xffff0000, v129
	v_pk_add_f32 v[162:163], v[120:121], v[128:129]
	global_load_dwordx2 v[120:121], v[70:71], off offset:-1024 nt
	v_pk_add_f32 v[160:161], v[132:133], v[134:135]
	v_lshlrev_b32_e32 v128, 16, v122
	v_and_b32_e32 v129, 0xffff0000, v122
	v_lshlrev_b32_e32 v122, 16, v123
	v_and_b32_e32 v123, 0xffff0000, v123
	s_waitcnt vmcnt(0)
	v_lshlrev_b32_e32 v132, 16, v120
	v_and_b32_e32 v133, 0xffff0000, v120
	v_lshlrev_b32_e32 v120, 16, v121
	v_and_b32_e32 v121, 0xffff0000, v121
	v_pk_add_f32 v[134:135], v[122:123], v[120:121]
	global_load_dwordx2 v[120:121], v[70:71], off offset:-512 nt
	v_pk_add_f32 v[132:133], v[128:129], v[132:133]
	v_lshlrev_b32_e32 v122, 16, v130
	v_and_b32_e32 v123, 0xffff0000, v130
	s_waitcnt vmcnt(0)
	v_lshlrev_b32_e32 v128, 16, v120
	v_and_b32_e32 v129, 0xffff0000, v120
	v_pk_add_f32 v[128:129], v[122:123], v[128:129]
	v_lshlrev_b32_e32 v122, 16, v131
	v_and_b32_e32 v123, 0xffff0000, v131
	v_lshlrev_b32_e32 v120, 16, v121
	v_and_b32_e32 v121, 0xffff0000, v121
	v_pk_add_f32 v[130:131], v[122:123], v[120:121]
	global_load_dwordx2 v[122:123], v[70:71], off nt
	v_lshlrev_b32_e32 v120, 16, v138
	v_and_b32_e32 v121, 0xffff0000, v138
	v_lshlrev_b32_e32 v138, 16, v139
	v_and_b32_e32 v139, 0xffff0000, v139
	v_lshl_add_u64 v[70:71], v[70:71], 0, s[76:77]
	s_waitcnt vmcnt(0)
	v_lshlrev_b32_e32 v146, 16, v122
	v_and_b32_e32 v147, 0xffff0000, v122
	v_pk_add_f32 v[120:121], v[120:121], v[146:147]
	v_lshlrev_b32_e32 v122, 16, v123
	v_and_b32_e32 v123, 0xffff0000, v123
	v_mov_b32_e32 v146, v149
	v_mov_b32_e32 v147, v151
	v_pk_add_f32 v[122:123], v[138:139], v[122:123]
	v_mov_b32_e32 v138, v148
	v_mov_b32_e32 v139, v150
	v_pk_mul_f32 v[146:147], v[146:147], v[146:147]
	v_pk_mul_f32 v[194:195], v[122:123], v[122:123]
	v_pk_fma_f32 v[138:139], v[138:139], v[138:139], v[146:147]
	v_mov_b32_e32 v146, v102
	v_mov_b32_e32 v147, v104
	v_pk_fma_f32 v[146:147], v[146:147], v[146:147], v[168:169]
	v_pk_fma_f32 v[168:169], v[92:93], v[92:93], v[136:137] op_sel_hi:[1,1,0]
	v_mul_f32_e32 v136, v95, v95
	v_pk_add_f32 v[138:139], v[138:139], v[138:139] op_sel:[0,1] op_sel_hi:[1,0]
	v_pk_add_f32 v[146:147], v[146:147], v[146:147] op_sel:[0,1] op_sel_hi:[1,0]
	v_pk_fma_f32 v[170:171], v[94:95], v[94:95], v[136:137] op_sel_hi:[1,1,0]
	v_mov_b32_e32 v139, v172
	v_mov_b32_e32 v147, v173
	v_mov_b32_e32 v169, v188
	v_mov_b32_e32 v171, v189
	v_pk_add_f32 v[138:139], v[138:139], v[146:147]
	v_pk_add_f32 v[146:147], v[168:169], v[170:171]
	v_mov_b32_e32 v168, v153
	v_mov_b32_e32 v169, v155
	v_pk_add_f32 v[138:139], v[138:139], v[146:147]
	v_mov_b32_e32 v146, v152
	v_mov_b32_e32 v147, v154
	v_pk_mul_f32 v[168:169], v[168:169], v[168:169]
	v_mov_b32_e32 v170, v113
	v_mov_b32_e32 v171, v115
	v_pk_fma_f32 v[146:147], v[146:147], v[146:147], v[168:169]
	v_mov_b32_e32 v168, v112
	v_mov_b32_e32 v169, v114
	v_pk_mul_f32 v[170:171], v[170:171], v[170:171]
	v_mul_f32_e32 v136, v99, v99
	v_pk_fma_f32 v[168:169], v[168:169], v[168:169], v[170:171]
	v_pk_fma_f32 v[170:171], v[98:99], v[98:99], v[136:137] op_sel_hi:[1,1,0]
	v_mul_f32_e32 v136, v101, v101
	v_pk_add_f32 v[146:147], v[146:147], v[146:147] op_sel:[0,1] op_sel_hi:[1,0]
	v_pk_add_f32 v[168:169], v[168:169], v[168:169] op_sel:[0,1] op_sel_hi:[1,0]
	v_pk_fma_f32 v[172:173], v[100:101], v[100:101], v[136:137] op_sel_hi:[1,1,0]
	v_pk_mul_f32 v[188:189], v[88:89], v[88:89]
	v_mov_b32_e32 v171, v190
	v_mov_b32_e32 v147, v188
	v_mov_b32_e32 v169, v189
	v_mov_b32_e32 v173, v191
	v_pk_add_f32 v[146:147], v[146:147], v[168:169]
	v_pk_add_f32 v[168:169], v[170:171], v[172:173]
	v_mov_b32_e32 v170, v157
	v_pk_add_f32 v[146:147], v[146:147], v[168:169]
	v_mov_b32_e32 v169, v138
	v_mov_b32_e32 v168, v146
	v_mov_b32_e32 v138, v147
	v_mov_b32_e32 v171, v159
	v_pk_add_f32 v[138:139], v[168:169], v[138:139]
	v_mov_b32_e32 v168, v156
	v_mov_b32_e32 v169, v158
	v_pk_mul_f32 v[170:171], v[170:171], v[170:171]
	v_mov_b32_e32 v172, v125
	v_mov_b32_e32 v173, v127
	ds_bpermute_b32 v147, v141, v139
	ds_bpermute_b32 v146, v141, v138
	v_pk_fma_f32 v[168:169], v[168:169], v[168:169], v[170:171]
	v_mov_b32_e32 v170, v124
	v_mov_b32_e32 v171, v126
	v_pk_mul_f32 v[172:173], v[172:173], v[172:173]
	v_mul_f32_e32 v136, v117, v117
	v_pk_fma_f32 v[170:171], v[170:171], v[170:171], v[172:173]
	v_pk_fma_f32 v[172:173], v[116:117], v[116:117], v[136:137] op_sel_hi:[1,1,0]
	v_mul_f32_e32 v136, v119, v119
	v_pk_add_f32 v[168:169], v[168:169], v[168:169] op_sel:[0,1] op_sel_hi:[1,0]
	v_pk_add_f32 v[170:171], v[170:171], v[170:171] op_sel:[0,1] op_sel_hi:[1,0]
	v_pk_fma_f32 v[188:189], v[118:119], v[118:119], v[136:137] op_sel_hi:[1,1,0]
	v_pk_mul_f32 v[190:191], v[106:107], v[106:107]
	v_mov_b32_e32 v173, v192
	v_mov_b32_e32 v169, v190
	v_mov_b32_e32 v171, v191
	v_mov_b32_e32 v189, v193
	v_pk_add_f32 v[168:169], v[168:169], v[170:171]
	v_pk_add_f32 v[170:171], v[172:173], v[188:189]
	v_mov_b32_e32 v172, v161
	v_mov_b32_e32 v173, v163
	s_waitcnt lgkmcnt(0)
	v_pk_add_f32 v[138:139], v[138:139], v[146:147]
	v_pk_add_f32 v[168:169], v[168:169], v[170:171]
	v_mov_b32_e32 v170, v160
	v_mov_b32_e32 v171, v162
	v_pk_mul_f32 v[172:173], v[172:173], v[172:173]
	v_mov_b32_e32 v188, v133
	v_mov_b32_e32 v189, v135
	ds_bpermute_b32 v147, v143, v139
	ds_bpermute_b32 v146, v143, v138
	v_pk_fma_f32 v[170:171], v[170:171], v[170:171], v[172:173]
	v_mov_b32_e32 v172, v132
	v_mov_b32_e32 v173, v134
	v_pk_mul_f32 v[188:189], v[188:189], v[188:189]
	v_mul_f32_e32 v136, v129, v129
	v_pk_fma_f32 v[172:173], v[172:173], v[172:173], v[188:189]
	v_pk_fma_f32 v[188:189], v[128:129], v[128:129], v[136:137] op_sel_hi:[1,1,0]
	v_mul_f32_e32 v136, v131, v131
	v_pk_add_f32 v[170:171], v[170:171], v[170:171] op_sel:[0,1] op_sel_hi:[1,0]
	v_pk_add_f32 v[172:173], v[172:173], v[172:173] op_sel:[0,1] op_sel_hi:[1,0]
	v_pk_fma_f32 v[190:191], v[130:131], v[130:131], v[136:137] op_sel_hi:[1,1,0]
	v_pk_mul_f32 v[192:193], v[120:121], v[120:121]
	v_mov_b32_e32 v189, v194
	v_mov_b32_e32 v171, v192
	v_mov_b32_e32 v173, v193
	v_mov_b32_e32 v191, v195
	v_pk_add_f32 v[170:171], v[170:171], v[172:173]
	v_pk_add_f32 v[172:173], v[188:189], v[190:191]
	s_waitcnt lgkmcnt(0)
	v_pk_add_f32 v[138:139], v[138:139], v[146:147]
	v_pk_add_f32 v[170:171], v[170:171], v[172:173]
	ds_bpermute_b32 v147, v145, v139
	ds_bpermute_b32 v146, v145, v138
	v_mov_b32_e32 v172, v170
	v_mov_b32_e32 v173, v168
	v_mov_b32_e32 v168, v171
	v_pk_add_f32 v[168:169], v[172:173], v[168:169]
	ds_bpermute_b32 v171, v141, v169
	ds_bpermute_b32 v170, v141, v168
	s_waitcnt lgkmcnt(2)
	v_pk_add_f32 v[138:139], v[138:139], v[146:147]
	ds_bpermute_b32 v147, v164, v139
	ds_bpermute_b32 v146, v164, v138
	s_waitcnt lgkmcnt(2)
	v_pk_add_f32 v[168:169], v[168:169], v[170:171]
	ds_bpermute_b32 v171, v143, v169
	ds_bpermute_b32 v170, v143, v168
	s_waitcnt lgkmcnt(2)
	v_pk_add_f32 v[138:139], v[138:139], v[146:147]
	ds_bpermute_b32 v147, v165, v139
	ds_bpermute_b32 v146, v165, v138
	s_waitcnt lgkmcnt(2)
	v_pk_add_f32 v[168:169], v[168:169], v[170:171]
	ds_bpermute_b32 v171, v145, v169
	ds_bpermute_b32 v170, v145, v168
	s_waitcnt lgkmcnt(2)
	v_pk_add_f32 v[138:139], v[138:139], v[146:147]
	ds_bpermute_b32 v147, v166, v139
	ds_bpermute_b32 v146, v166, v138
	s_waitcnt lgkmcnt(2)
	v_pk_add_f32 v[168:169], v[168:169], v[170:171]
	ds_bpermute_b32 v171, v164, v169
	ds_bpermute_b32 v170, v164, v168
	s_waitcnt lgkmcnt(2)
	v_pk_add_f32 v[138:139], v[138:139], v[146:147]
	v_mov_b64_e32 v[146:147], s[90:91]
	v_pk_fma_f32 v[138:139], v[138:139], s[82:83], v[146:147] op_sel_hi:[1,0,0]
	s_waitcnt lgkmcnt(0)
	v_pk_add_f32 v[168:169], v[168:169], v[170:171]
	v_mul_f32_e32 v65, 0x4b800000, v139
	v_cmp_gt_f32_e64 s[4:5], s81, v139
	ds_bpermute_b32 v171, v165, v169
	ds_bpermute_b32 v170, v165, v168
	v_cndmask_b32_e64 v65, v139, v65, s[4:5]
	v_rsq_f32_e32 v65, v65
	v_cmp_gt_f32_e32 vcc, s81, v138
	s_waitcnt lgkmcnt(0)
	v_pk_add_f32 v[168:169], v[168:169], v[170:171]
	v_mul_f32_e32 v75, 0x45800000, v65
	v_cndmask_b32_e64 v140, v65, v75, s[4:5]
	v_mul_f32_e32 v65, 0x4b800000, v138
	ds_bpermute_b32 v171, v166, v169
	ds_bpermute_b32 v170, v166, v168
	v_cndmask_b32_e32 v65, v138, v65, vcc
	v_rsq_f32_e32 v65, v65
	v_pk_mul_f32 v[150:151], v[150:151], v[140:141] op_sel_hi:[1,0]
	v_pk_mul_f32 v[148:149], v[148:149], v[140:141] op_sel_hi:[1,0]
	s_waitcnt lgkmcnt(0)
	v_pk_add_f32 v[168:169], v[168:169], v[170:171]
	v_mul_f32_e32 v75, 0x45800000, v65
	v_pk_fma_f32 v[146:147], v[168:169], s[82:83], v[146:147] op_sel_hi:[1,0,0]
	v_cndmask_b32_e32 v138, v65, v75, vcc
	v_mul_f32_e32 v65, 0x4b800000, v147
	v_cmp_gt_f32_e64 s[4:5], s81, v147
	v_cmp_gt_f32_e32 vcc, s81, v146
	global_load_dwordx4 v[168:171], v[66:67], off
	v_cndmask_b32_e64 v65, v147, v65, s[4:5]
	v_rsq_f32_e32 v65, v65
	s_waitcnt vmcnt(0)
	v_pk_mul_f32 v[148:149], v[148:149], v[168:169]
	v_mul_f32_e32 v75, 0x45800000, v65
	v_cndmask_b32_e64 v144, v65, v75, s[4:5]
	v_mul_f32_e32 v65, 0x4b800000, v146
	v_cndmask_b32_e32 v65, v146, v65, vcc
	v_rsq_f32_e32 v65, v65
	v_pk_mul_f32 v[150:151], v[150:151], v[170:171]
	v_mul_f32_e32 v75, 0x45800000, v65
	v_cndmask_b32_e32 v142, v65, v75, vcc
	v_add_u32_e32 v65, 0x2000, v64
	v_lshrrev_b32_e32 v65, 12, v65
	v_mad_u32_u24 v65, v65, s83, s83
	v_cmp_lt_i32_e32 vcc, s2, v64
	v_mov_b32_e32 v75, v137
	v_add_u32_e32 v64, s68, v64
	v_cndmask_b32_e32 v136, 0, v65, vcc
	v_lshl_add_u64 v[146:147], v[136:137], 2, s[84:85]
	v_lshl_add_u64 v[146:147], v[146:147], 0, s[62:63]
	v_lshl_add_u64 v[172:173], v[146:147], 0, v[74:75]
	global_load_dwordx4 v[188:191], v[172:173], off
	v_cmp_lt_i32_e32 vcc, s60, v64
	s_or_b64 s[8:9], vcc, s[8:9]
	s_waitcnt vmcnt(0)
	v_pk_fma_f32 v[50:51], v[190:191], v[150:151], v[50:51]
	v_pk_fma_f32 v[48:49], v[188:189], v[148:149], v[48:49]
	global_store_dwordx4 v[72:73], v[48:51], off offset:-3072 nt
	s_nop 1
	v_pk_mul_f32 v[48:49], v[154:155], v[138:139] op_sel_hi:[1,0]
	v_pk_mul_f32 v[50:51], v[152:153], v[138:139] op_sel_hi:[1,0]
	v_pk_mul_f32 v[48:49], v[48:49], v[170:171]
	v_pk_mul_f32 v[148:149], v[50:51], v[168:169]
	v_pk_fma_f32 v[50:51], v[190:191], v[48:49], v[54:55]
	v_pk_fma_f32 v[48:49], v[188:189], v[148:149], v[52:53]
	global_store_dwordx4 v[86:87], v[48:51], off nt
	s_nop 1
	v_pk_mul_f32 v[48:49], v[158:159], v[144:145] op_sel_hi:[1,0]
	v_pk_mul_f32 v[50:51], v[156:157], v[144:145] op_sel_hi:[1,0]
	v_pk_mul_f32 v[48:49], v[170:171], v[48:49]
	v_pk_mul_f32 v[52:53], v[168:169], v[50:51]
	v_pk_fma_f32 v[50:51], v[190:191], v[48:49], v[58:59]
	v_pk_fma_f32 v[48:49], v[188:189], v[52:53], v[56:57]
	global_store_dwordx4 v[96:97], v[48:51], off nt
	v_pk_mul_f32 v[56:57], v[102:103], v[140:141] op_sel_hi:[1,0]
	v_pk_mul_f32 v[58:59], v[104:105], v[140:141] op_sel_hi:[1,0]
	v_pk_mul_f32 v[48:49], v[162:163], v[142:143] op_sel_hi:[1,0]
	v_pk_mul_f32 v[50:51], v[160:161], v[142:143] op_sel_hi:[1,0]
	v_pk_mul_f32 v[48:49], v[170:171], v[48:49]
	v_pk_mul_f32 v[52:53], v[168:169], v[50:51]
	v_pk_fma_f32 v[50:51], v[190:191], v[48:49], v[62:63]
	v_pk_fma_f32 v[48:49], v[188:189], v[52:53], v[60:61]
	global_store_dwordx4 v[110:111], v[48:51], off nt
	global_load_dwordx4 v[48:51], v[66:67], off offset:1024
	v_lshl_add_u64 v[52:53], v[146:147], 0, v[76:77]
	global_load_dwordx4 v[52:55], v[52:53], off
	s_waitcnt vmcnt(1)
	v_pk_mul_f32 v[58:59], v[58:59], v[50:51]
	v_pk_mul_f32 v[56:57], v[56:57], v[48:49]
	s_waitcnt vmcnt(0)
	v_pk_fma_f32 v[18:19], v[54:55], v[58:59], v[18:19]
	v_pk_fma_f32 v[16:17], v[52:53], v[56:57], v[16:17]
	global_store_dwordx4 v[72:73], v[16:19], off offset:-2048 nt
	s_nop 1
	v_pk_mul_f32 v[16:17], v[112:113], v[138:139] op_sel_hi:[1,0]
	v_pk_mul_f32 v[18:19], v[114:115], v[138:139] op_sel_hi:[1,0]
	v_pk_mul_f32 v[16:17], v[16:17], v[48:49]
	v_pk_mul_f32 v[18:19], v[18:19], v[50:51]
	v_pk_fma_f32 v[16:17], v[52:53], v[16:17], v[24:25]
	v_pk_fma_f32 v[18:19], v[54:55], v[18:19], v[26:27]
	global_store_dwordx4 v[86:87], v[16:19], off offset:1024 nt
	v_lshl_add_u64 v[24:25], v[146:147], 0, v[78:79]
	s_nop 0
	v_pk_mul_f32 v[16:17], v[124:125], v[144:145] op_sel_hi:[1,0]
	v_pk_mul_f32 v[18:19], v[126:127], v[144:145] op_sel_hi:[1,0]
	v_pk_mul_f32 v[16:17], v[16:17], v[48:49]
	v_pk_mul_f32 v[18:19], v[18:19], v[50:51]
	v_pk_fma_f32 v[16:17], v[52:53], v[16:17], v[36:37]
	v_pk_fma_f32 v[18:19], v[54:55], v[18:19], v[38:39]
	global_store_dwordx4 v[96:97], v[16:19], off offset:1024 nt
	v_pk_mul_f32 v[36:37], v[92:93], v[140:141] op_sel_hi:[1,0]
	v_pk_mul_f32 v[38:39], v[94:95], v[140:141] op_sel_hi:[1,0]
	v_pk_mul_f32 v[16:17], v[132:133], v[142:143] op_sel_hi:[1,0]
	v_pk_mul_f32 v[18:19], v[134:135], v[142:143] op_sel_hi:[1,0]
	v_pk_mul_f32 v[16:17], v[48:49], v[16:17]
	v_pk_mul_f32 v[18:19], v[50:51], v[18:19]
	v_pk_fma_f32 v[16:17], v[52:53], v[16:17], v[44:45]
	v_pk_fma_f32 v[18:19], v[54:55], v[18:19], v[46:47]
	global_store_dwordx4 v[110:111], v[16:19], off offset:1024 nt
	global_load_dwordx4 v[16:19], v[66:67], off offset:2048
	s_waitcnt vmcnt(0)
	v_pk_mul_f32 v[38:39], v[38:39], v[18:19]
	global_load_dwordx4 v[24:27], v[24:25], off
	v_pk_mul_f32 v[36:37], v[36:37], v[16:17]
	s_waitcnt vmcnt(0)
	v_pk_fma_f32 v[10:11], v[26:27], v[38:39], v[10:11]
	v_pk_fma_f32 v[8:9], v[24:25], v[36:37], v[8:9]
	global_store_dwordx4 v[72:73], v[8:11], off offset:-1024 nt
	s_nop 1
	v_pk_mul_f32 v[8:9], v[98:99], v[138:139] op_sel_hi:[1,0]
	v_pk_mul_f32 v[10:11], v[100:101], v[138:139] op_sel_hi:[1,0]
	v_pk_mul_f32 v[8:9], v[8:9], v[16:17]
	v_pk_mul_f32 v[10:11], v[10:11], v[18:19]
	v_pk_fma_f32 v[8:9], v[24:25], v[8:9], v[12:13]
	v_pk_fma_f32 v[10:11], v[26:27], v[10:11], v[14:15]
	global_store_dwordx4 v[86:87], v[8:11], off offset:2048 nt
	v_lshl_add_u64 v[12:13], v[146:147], 0, v[80:81]
	s_nop 0
	v_pk_mul_f32 v[8:9], v[116:117], v[144:145] op_sel_hi:[1,0]
	v_pk_mul_f32 v[10:11], v[118:119], v[144:145] op_sel_hi:[1,0]
	v_pk_mul_f32 v[8:9], v[8:9], v[16:17]
	v_pk_mul_f32 v[10:11], v[10:11], v[18:19]
	v_pk_fma_f32 v[8:9], v[24:25], v[8:9], v[28:29]
	v_pk_fma_f32 v[10:11], v[26:27], v[10:11], v[30:31]
	global_store_dwordx4 v[96:97], v[8:11], off offset:2048 nt
	s_nop 1
	v_pk_mul_f32 v[8:9], v[128:129], v[142:143] op_sel_hi:[1,0]
	v_pk_mul_f32 v[10:11], v[130:131], v[142:143] op_sel_hi:[1,0]
	v_pk_mul_f32 v[8:9], v[8:9], v[16:17]
	v_pk_mul_f32 v[10:11], v[10:11], v[18:19]
	v_pk_fma_f32 v[8:9], v[24:25], v[8:9], v[40:41]
	v_pk_fma_f32 v[10:11], v[26:27], v[10:11], v[42:43]
	global_store_dwordx4 v[110:111], v[8:11], off offset:2048 nt
	global_load_dwordx4 v[8:11], v[66:67], off offset:3072
	v_pk_mul_f32 v[16:17], v[82:83], v[140:141] op_sel_hi:[1,0]
	global_load_dwordx4 v[12:15], v[12:13], off
	v_pk_mul_f32 v[18:19], v[84:85], v[140:141] op_sel_hi:[1,0]
	s_waitcnt vmcnt(1)
	v_pk_mul_f32 v[16:17], v[16:17], v[8:9]
	v_pk_mul_f32 v[18:19], v[18:19], v[10:11]
	s_waitcnt vmcnt(0)
	v_pk_fma_f32 v[0:1], v[12:13], v[16:17], v[0:1]
	v_pk_fma_f32 v[2:3], v[14:15], v[18:19], v[2:3]
	global_store_dwordx4 v[72:73], v[0:3], off nt
	v_lshl_add_u64 v[72:73], v[72:73], 0, s[72:73]
	s_nop 0
	v_pk_mul_f32 v[0:1], v[88:89], v[138:139] op_sel_hi:[1,0]
	v_pk_mul_f32 v[2:3], v[90:91], v[138:139] op_sel_hi:[1,0]
	v_pk_mul_f32 v[0:1], v[0:1], v[8:9]
	v_pk_mul_f32 v[2:3], v[2:3], v[10:11]
	v_pk_fma_f32 v[0:1], v[12:13], v[0:1], v[4:5]
	v_pk_fma_f32 v[2:3], v[14:15], v[2:3], v[6:7]
	global_store_dwordx4 v[86:87], v[0:3], off offset:3072 nt
	s_nop 1
	v_pk_mul_f32 v[0:1], v[106:107], v[144:145] op_sel_hi:[1,0]
	v_pk_mul_f32 v[2:3], v[108:109], v[144:145] op_sel_hi:[1,0]
	v_pk_mul_f32 v[0:1], v[0:1], v[8:9]
	v_pk_mul_f32 v[2:3], v[2:3], v[10:11]
	v_pk_fma_f32 v[0:1], v[12:13], v[0:1], v[20:21]
	v_pk_fma_f32 v[2:3], v[14:15], v[2:3], v[22:23]
	global_store_dwordx4 v[96:97], v[0:3], off offset:3072 nt
	s_nop 1
	v_pk_mul_f32 v[0:1], v[120:121], v[142:143] op_sel_hi:[1,0]
	v_pk_mul_f32 v[2:3], v[122:123], v[142:143] op_sel_hi:[1,0]
	v_pk_mul_f32 v[0:1], v[0:1], v[8:9]
	v_pk_mul_f32 v[2:3], v[2:3], v[10:11]
	v_pk_fma_f32 v[0:1], v[12:13], v[0:1], v[32:33]
	v_pk_fma_f32 v[2:3], v[14:15], v[2:3], v[34:35]
	global_store_dwordx4 v[110:111], v[0:3], off offset:3072 nt
	s_andn2_b64 exec, exec, s[8:9]
	s_cbranch_execnz .LBB0_1522

.LBB0_1534:
	v_cmp_gt_i32_e32 vcc, s12, v76
	v_add_u32_e32 v72, 0xffffdfff, v82
	v_lshl_add_u64 v[0:1], v[82:83], 0, -1
	v_cndmask_b32_e32 v1, 0, v1, vcc
	v_cndmask_b32_e32 v0, v72, v0, vcc
	v_mov_b32_e32 v22, s19
	v_mov_b32_e32 v23, s17
	v_mov_b32_e32 v48, s18
	v_mov_b32_e32 v49, s16
	v_cndmask_b32_e32 v3, v22, v23, vcc
	v_cndmask_b32_e32 v2, v48, v49, vcc
	v_lshlrev_b64 v[0:1], 12, v[0:1]
	s_mov_b32 s2, 0xfb9ff000
	v_lshl_add_u64 v[0:1], v[2:3], 0, v[0:1]
	v_add_co_u32_e64 v4, s[4:5], s2, v86
	v_lshl_add_u64 v[0:1], v[0:1], 0, v[136:137]
	s_nop 0
	v_addc_co_u32_e64 v5, s[4:5], -1, v87, s[4:5]
	global_load_dwordx4 v[40:43], v[0:1], off nt
	global_load_dwordx2 v[122:123], v[4:5], off offset:-3584 nt
	global_load_dwordx4 v[28:31], v[0:1], off offset:1024 nt
	global_load_dwordx2 v[120:121], v[4:5], off offset:-3072 nt
	global_load_dwordx4 v[12:15], v[0:1], off offset:2048 nt
	global_load_dwordx2 v[118:119], v[4:5], off offset:-2560 nt
	s_nop 0
	global_load_dwordx4 v[0:3], v[0:1], off offset:3072 nt
	s_nop 0
	global_load_dwordx2 v[6:7], v[4:5], off offset:-2048 nt
	v_cmp_gt_i32_e64 s[4:5], s12, v82
	s_mov_b32 s2, 0xfba00000
	v_add_u32_e32 v10, 0xffffe001, v82
	v_cndmask_b32_e64 v9, v22, v23, s[4:5]
	v_cndmask_b32_e64 v8, v48, v49, s[4:5]
	v_add_u32_e32 v50, 0xffffe002, v82
	v_mov_b32_e32 v93, v137
	v_mov_b32_e32 v95, v137
	v_add_u32_e32 v76, s68, v76
	s_waitcnt vmcnt(6)
	v_and_b32_e32 v149, 0xffff0000, v123
	v_and_b32_e32 v147, 0xffff0000, v122
	v_lshlrev_b32_e32 v148, 16, v123
	v_mul_f32_e32 v74, v149, v149
	s_waitcnt vmcnt(4)
	v_and_b32_e32 v129, 0xffff0000, v121
	v_and_b32_e32 v128, 0xffff0000, v120
	s_waitcnt vmcnt(0)
	v_lshlrev_b32_e32 v75, 16, v6
	v_and_b32_e32 v73, 0xffff0000, v6
	v_add_u32_e32 v6, 0xffffe000, v82
	v_lshlrev_b32_e32 v96, 16, v7
	v_and_b32_e32 v97, 0xffff0000, v7
	v_cndmask_b32_e64 v7, 0, v83, s[4:5]
	v_cndmask_b32_e64 v6, v6, v82, s[4:5]
	v_lshlrev_b64 v[6:7], 12, v[6:7]
	v_lshl_add_u64 v[6:7], v[8:9], 0, v[6:7]
	v_add_co_u32_e64 v110, s[4:5], s2, v86
	v_lshl_add_u64 v[6:7], v[6:7], 0, v[136:137]
	s_nop 0
	v_addc_co_u32_e64 v111, s[4:5], -1, v87, s[4:5]
	global_load_dwordx4 v[44:47], v[6:7], off nt
	global_load_dwordx2 v[124:125], v[4:5], off offset:-1536 nt
	global_load_dwordx4 v[32:35], v[6:7], off offset:1024 nt
	global_load_dwordx2 v[116:117], v[4:5], off offset:-1024 nt
	global_load_dwordx4 v[16:19], v[6:7], off offset:2048 nt
	global_load_dwordx2 v[70:71], v[4:5], off offset:-512 nt
	s_nop 0
	global_load_dwordx4 v[4:7], v[6:7], off offset:3072 nt
	v_lshlrev_b32_e32 v146, 16, v122
	global_load_dwordx2 v[8:9], v[110:111], off offset:-4096 nt
	v_pk_fma_f32 v[126:127], v[148:149], v[148:149], v[74:75] op_sel_hi:[1,1,0]
	v_lshlrev_b32_e32 v131, 16, v121
	v_lshlrev_b32_e32 v130, 16, v120
	v_pk_mul_f32 v[120:121], v[128:129], v[128:129]
	v_mul_f32_e32 v74, v147, v147
	v_pk_fma_f32 v[132:133], v[130:131], v[130:131], v[120:121]
	v_lshlrev_b32_e32 v120, 16, v118
	v_and_b32_e32 v121, 0xffff0000, v118
	v_lshlrev_b32_e32 v122, 16, v119
	v_and_b32_e32 v123, 0xffff0000, v119
	v_pk_fma_f32 v[118:119], v[146:147], v[146:147], v[74:75] op_sel_hi:[1,1,0]
	v_mov_b32_e32 v134, v126
	v_mov_b32_e32 v74, v118
	v_mov_b32_e32 v135, v75
	v_pk_add_f32 v[118:119], v[118:119], v[126:127]
	v_pk_mul_f32 v[126:127], v[74:75], v[134:135]
	v_mul_f32_e32 v77, v73, v73
	v_mov_b32_e32 v119, v127
	v_pk_add_f32 v[126:127], v[132:133], v[132:133] op_sel:[0,1] op_sel_hi:[1,0]
	v_mul_f32_e32 v74, v121, v121
	v_mov_b32_e32 v127, v77
	v_pk_add_f32 v[118:119], v[118:119], v[126:127]
	v_pk_fma_f32 v[126:127], v[120:121], v[120:121], v[74:75] op_sel_hi:[1,1,0]
	v_mul_f32_e32 v74, v123, v123
	v_mul_f32_e32 v89, v96, v96
	v_mul_f32_e32 v91, v97, v97
	v_pk_fma_f32 v[132:133], v[122:123], v[122:123], v[74:75] op_sel_hi:[1,1,0]
	v_mov_b32_e32 v127, v89
	v_mov_b32_e32 v133, v91
	v_pk_add_f32 v[126:127], v[126:127], v[132:133]
	s_mov_b64 s[2:3], 0x2000
	v_pk_add_f32 v[118:119], v[118:119], v[126:127]
	s_waitcnt vmcnt(6)
	v_and_b32_e32 v151, 0xffff0000, v124
	v_and_b32_e32 v153, 0xffff0000, v125
	v_lshlrev_b32_e32 v150, 16, v124
	v_lshlrev_b32_e32 v152, 16, v125
	v_mul_f32_e32 v74, v153, v153
	s_waitcnt vmcnt(4)
	v_and_b32_e32 v133, 0xffff0000, v117
	v_and_b32_e32 v132, 0xffff0000, v116
	s_waitcnt vmcnt(0)
	v_lshlrev_b32_e32 v101, 16, v8
	v_and_b32_e32 v99, 0xffff0000, v8
	v_lshlrev_b32_e32 v102, 16, v9
	v_and_b32_e32 v103, 0xffff0000, v9
	v_lshl_add_u64 v[8:9], v[82:83], 0, 1
	v_cmp_gt_i32_e64 s[4:5], s12, v8
	v_lshlrev_b32_e32 v124, 16, v70
	v_and_b32_e32 v125, 0xffff0000, v70
	v_cndmask_b32_e64 v9, 0, v9, s[4:5]
	v_cndmask_b32_e64 v8, v10, v8, s[4:5]
	v_cndmask_b32_e64 v11, v22, v23, s[4:5]
	v_cndmask_b32_e64 v10, v48, v49, s[4:5]
	v_lshlrev_b64 v[8:9], 12, v[8:9]
	v_lshl_add_u64 v[8:9], v[10:11], 0, v[8:9]
	v_lshl_add_u64 v[8:9], v[8:9], 0, v[136:137]
	global_load_dwordx4 v[52:55], v[8:9], off nt
	global_load_dwordx2 v[68:69], v[110:111], off offset:-3584 nt
	global_load_dwordx4 v[36:39], v[8:9], off offset:1024 nt
	global_load_dwordx2 v[66:67], v[110:111], off offset:-3072 nt
	global_load_dwordx4 v[24:27], v[8:9], off offset:2048 nt
	global_load_dwordx2 v[64:65], v[110:111], off offset:-2560 nt
	s_nop 0
	global_load_dwordx4 v[8:11], v[8:9], off offset:3072 nt
	s_nop 0
	global_load_dwordx2 v[20:21], v[110:111], off offset:-2048 nt
	v_mul_f32_e32 v70, v151, v151
	v_pk_fma_f32 v[138:139], v[152:153], v[152:153], v[74:75] op_sel_hi:[1,1,0]
	v_lshlrev_b32_e32 v135, 16, v117
	v_lshlrev_b32_e32 v134, 16, v116
	v_pk_mul_f32 v[116:117], v[132:133], v[132:133]
	v_lshlrev_b32_e32 v126, 16, v71
	v_and_b32_e32 v127, 0xffff0000, v71
	v_pk_fma_f32 v[70:71], v[150:151], v[150:151], v[70:71] op_sel_hi:[1,1,0]
	v_pk_fma_f32 v[116:117], v[134:135], v[134:135], v[116:117]
	v_mov_b32_e32 v100, v70
	v_mov_b32_e32 v140, v138
	v_mov_b32_e32 v141, v101
	v_mul_f32_e32 v74, v99, v99
	v_pk_add_f32 v[70:71], v[70:71], v[138:139]
	v_pk_mul_f32 v[138:139], v[100:101], v[140:141]
	v_pk_add_f32 v[116:117], v[116:117], v[116:117] op_sel:[0,1] op_sel_hi:[1,0]
	v_mov_b32_e32 v71, v139
	v_mov_b32_e32 v117, v74
	v_mul_f32_e32 v74, v125, v125
	v_pk_add_f32 v[70:71], v[70:71], v[116:117]
	v_pk_fma_f32 v[116:117], v[124:125], v[124:125], v[74:75] op_sel_hi:[1,1,0]
	v_mul_f32_e32 v74, v127, v127
	v_mul_f32_e32 v77, v102, v102
	v_mul_f32_e32 v89, v103, v103
	v_pk_fma_f32 v[138:139], v[126:127], v[126:127], v[74:75] op_sel_hi:[1,1,0]
	v_mov_b32_e32 v117, v77
	v_mov_b32_e32 v139, v89
	v_pk_add_f32 v[116:117], v[116:117], v[138:139]
	s_waitcnt vmcnt(6)
	v_and_b32_e32 v163, 0xffff0000, v68
	v_pk_add_f32 v[70:71], v[70:71], v[116:117]
	v_mov_b32_e32 v117, v118
	v_mov_b32_e32 v116, v70
	v_mov_b32_e32 v118, v71
	v_pk_add_f32 v[70:71], v[116:117], v[118:119]
	s_waitcnt vmcnt(0)
	v_lshlrev_b32_e32 v107, 16, v20
	v_and_b32_e32 v105, 0xffff0000, v20
	v_lshlrev_b32_e32 v108, 16, v21
	v_and_b32_e32 v109, 0xffff0000, v21
	v_lshl_add_u64 v[20:21], v[82:83], 0, 2
	v_cmp_gt_i32_e64 s[4:5], s12, v20
	ds_bpermute_b32 v117, v187, v71
	ds_bpermute_b32 v116, v187, v70
	v_cndmask_b32_e64 v21, 0, v21, s[4:5]
	v_cndmask_b32_e64 v20, v50, v20, s[4:5]
	v_cndmask_b32_e64 v23, v22, v23, s[4:5]
	v_cndmask_b32_e64 v22, v48, v49, s[4:5]
	v_lshlrev_b64 v[20:21], 12, v[20:21]
	v_lshl_add_u64 v[20:21], v[22:23], 0, v[20:21]
	v_lshl_add_u64 v[20:21], v[20:21], 0, v[136:137]
	global_load_dwordx4 v[56:59], v[20:21], off nt
	global_load_dwordx2 v[158:159], v[110:111], off offset:-1536 nt
	global_load_dwordx4 v[60:63], v[20:21], off offset:1024 nt
	global_load_dwordx2 v[142:143], v[110:111], off offset:-1024 nt
	global_load_dwordx4 v[48:51], v[20:21], off offset:2048 nt
	global_load_dwordx2 v[144:145], v[110:111], off offset:-512 nt
	s_nop 0
	global_load_dwordx4 v[20:23], v[20:21], off offset:3072 nt
	s_nop 0
	global_load_dwordx2 v[114:115], v[110:111], off nt
	s_waitcnt lgkmcnt(0)
	v_pk_add_f32 v[70:71], v[70:71], v[116:117]
	ds_bpermute_b32 v117, v188, v71
	ds_bpermute_b32 v116, v188, v70
	v_and_b32_e32 v165, 0xffff0000, v69
	v_lshlrev_b32_e32 v162, 16, v68
	v_lshlrev_b32_e32 v164, 16, v69
	v_mul_f32_e32 v68, v165, v165
	s_waitcnt lgkmcnt(0)
	v_pk_add_f32 v[70:71], v[70:71], v[116:117]
	ds_bpermute_b32 v117, v189, v71
	ds_bpermute_b32 v116, v189, v70
	v_and_b32_e32 v155, 0xffff0000, v67
	v_and_b32_e32 v154, 0xffff0000, v66
	v_lshlrev_b32_e32 v138, 16, v64
	v_and_b32_e32 v139, 0xffff0000, v64
	s_waitcnt lgkmcnt(0)
	v_pk_add_f32 v[70:71], v[70:71], v[116:117]
	ds_bpermute_b32 v117, v190, v71
	ds_bpermute_b32 v116, v190, v70
	v_mul_f32_e32 v64, v163, v163
	v_pk_fma_f32 v[68:69], v[164:165], v[164:165], v[68:69] op_sel_hi:[1,1,0]
	v_lshlrev_b32_e32 v157, 16, v67
	v_lshlrev_b32_e32 v156, 16, v66
	s_waitcnt lgkmcnt(0)
	v_pk_add_f32 v[70:71], v[70:71], v[116:117]
	ds_bpermute_b32 v117, v191, v71
	ds_bpermute_b32 v116, v191, v70
	v_pk_mul_f32 v[66:67], v[154:155], v[154:155]
	v_lshlrev_b32_e32 v140, 16, v65
	v_and_b32_e32 v141, 0xffff0000, v65
	v_pk_fma_f32 v[64:65], v[162:163], v[162:163], v[64:65] op_sel_hi:[1,1,0]
	s_waitcnt lgkmcnt(0)
	v_pk_add_f32 v[70:71], v[70:71], v[116:117]
	ds_bpermute_b32 v117, v192, v71
	ds_bpermute_b32 v116, v192, v70
	v_pk_fma_f32 v[66:67], v[156:157], v[156:157], v[66:67]
	v_mov_b32_e32 v106, v64
	v_mul_f32_e32 v77, v105, v105
	v_pk_add_f32 v[64:65], v[64:65], v[68:69]
	s_waitcnt lgkmcnt(0)
	v_pk_add_f32 v[70:71], v[70:71], v[116:117]
	v_mov_b64_e32 v[116:117], s[90:91]
	v_pk_fma_f32 v[70:71], v[70:71], s[82:83], v[116:117] op_sel_hi:[1,0,0]
	v_pk_add_f32 v[66:67], v[66:67], v[66:67] op_sel:[0,1] op_sel_hi:[1,0]
	v_mul_f32_e32 v74, 0x4b800000, v71
	v_cmp_gt_f32_e64 s[6:7], s81, v71
	v_cmp_gt_f32_e64 s[4:5], s81, v70
	v_mov_b32_e32 v67, v77
	v_cndmask_b32_e64 v71, v71, v74, s[6:7]
	v_rsq_f32_e32 v71, v71
	v_mul_f32_e32 v89, v108, v108
	v_mul_f32_e32 v91, v109, v109
	v_lshl_add_u64 v[82:83], v[82:83], 0, s[68:69]
	v_mul_f32_e32 v74, 0x45800000, v71
	v_cndmask_b32_e64 v98, v71, v74, s[6:7]
	v_mul_f32_e32 v71, 0x4b800000, v70
	v_cndmask_b32_e64 v70, v70, v71, s[4:5]
	v_rsq_f32_e32 v70, v70
	v_pk_mul_f32 v[148:149], v[98:99], v[148:149] op_sel_hi:[0,1]
	v_pk_mul_f32 v[146:147], v[98:99], v[146:147] op_sel_hi:[0,1]
	v_pk_mul_f32 v[96:97], v[98:99], v[96:97] op_sel_hi:[0,1]
	v_mul_f32_e32 v71, 0x45800000, v70
	v_cndmask_b32_e64 v74, v70, v71, s[4:5]
	v_mov_b32_e32 v70, v68
	v_mov_b32_e32 v71, v107
	v_pk_mul_f32 v[68:69], v[106:107], v[70:71]
	v_pk_mul_f32 v[150:151], v[74:75], v[150:151] op_sel_hi:[0,1]
	v_mov_b32_e32 v65, v69
	v_pk_add_f32 v[64:65], v[64:65], v[66:67]
	v_mul_f32_e32 v66, v139, v139
	v_mul_f32_e32 v68, v141, v141
	v_pk_fma_f32 v[66:67], v[138:139], v[138:139], v[66:67] op_sel_hi:[1,1,0]
	v_pk_fma_f32 v[68:69], v[140:141], v[140:141], v[68:69] op_sel_hi:[1,1,0]
	v_mov_b32_e32 v67, v89
	v_mov_b32_e32 v69, v91
	v_pk_add_f32 v[66:67], v[66:67], v[68:69]
	s_waitcnt vmcnt(6)
	v_and_b32_e32 v167, 0xffff0000, v158
	v_and_b32_e32 v169, 0xffff0000, v159
	v_pk_add_f32 v[64:65], v[64:65], v[66:67]
	v_lshlrev_b32_e32 v166, 16, v158
	v_lshlrev_b32_e32 v168, 16, v159
	v_mul_f32_e32 v66, v169, v169
	s_waitcnt vmcnt(4)
	v_and_b32_e32 v159, 0xffff0000, v143
	v_and_b32_e32 v158, 0xffff0000, v142
	v_mul_f32_e32 v70, v167, v167
	s_waitcnt vmcnt(0)
	v_lshlrev_b32_e32 v113, 16, v114
	v_pk_fma_f32 v[66:67], v[168:169], v[168:169], v[66:67] op_sel_hi:[1,1,0]
	v_lshlrev_b32_e32 v161, 16, v143
	v_lshlrev_b32_e32 v160, 16, v142
	v_pk_mul_f32 v[68:69], v[158:159], v[158:159]
	v_pk_fma_f32 v[70:71], v[166:167], v[166:167], v[70:71] op_sel_hi:[1,1,0]
	v_and_b32_e32 v111, 0xffff0000, v114
	v_pk_fma_f32 v[68:69], v[160:161], v[160:161], v[68:69]
	v_mov_b32_e32 v112, v70
	v_mov_b32_e32 v118, v66
	v_mov_b32_e32 v119, v113
	v_mul_f32_e32 v77, v111, v111
	v_pk_add_f32 v[66:67], v[70:71], v[66:67]
	v_pk_mul_f32 v[70:71], v[112:113], v[118:119]
	v_pk_add_f32 v[68:69], v[68:69], v[68:69] op_sel:[0,1] op_sel_hi:[1,0]
	v_lshlrev_b32_e32 v142, 16, v144
	v_and_b32_e32 v143, 0xffff0000, v144
	v_lshlrev_b32_e32 v144, 16, v145
	v_and_b32_e32 v145, 0xffff0000, v145
	v_mov_b32_e32 v67, v71
	v_mov_b32_e32 v69, v77
	v_lshlrev_b32_e32 v114, 16, v115
	v_and_b32_e32 v115, 0xffff0000, v115
	v_pk_add_f32 v[66:67], v[66:67], v[68:69]
	v_mul_f32_e32 v68, v143, v143
	v_mul_f32_e32 v70, v145, v145
	v_mul_f32_e32 v89, v114, v114
	v_mul_f32_e32 v91, v115, v115
	v_pk_fma_f32 v[68:69], v[142:143], v[142:143], v[68:69] op_sel_hi:[1,1,0]
	v_pk_fma_f32 v[70:71], v[144:145], v[144:145], v[70:71] op_sel_hi:[1,1,0]
	v_mov_b32_e32 v69, v89
	v_mov_b32_e32 v71, v91
	v_pk_add_f32 v[68:69], v[68:69], v[70:71]
	v_mov_b32_e32 v89, v137
	v_pk_add_f32 v[66:67], v[66:67], v[68:69]
	v_mov_b32_e32 v69, v64
	v_mov_b32_e32 v68, v66
	v_mov_b32_e32 v64, v67
	v_pk_add_f32 v[64:65], v[68:69], v[64:65]
	ds_bpermute_b32 v67, v187, v65
	ds_bpermute_b32 v66, v187, v64
	v_mov_b32_e32 v91, v137
	v_mov_b32_e32 v110, v113
	s_waitcnt lgkmcnt(0)
	v_pk_add_f32 v[64:65], v[64:65], v[66:67]
	ds_bpermute_b32 v67, v188, v65
	ds_bpermute_b32 v66, v188, v64
	s_waitcnt lgkmcnt(0)
	v_pk_add_f32 v[64:65], v[64:65], v[66:67]
	ds_bpermute_b32 v67, v189, v65
	ds_bpermute_b32 v66, v189, v64
	s_waitcnt lgkmcnt(0)
	v_pk_add_f32 v[64:65], v[64:65], v[66:67]
	ds_bpermute_b32 v67, v190, v65
	ds_bpermute_b32 v66, v190, v64
	s_waitcnt lgkmcnt(0)
	v_pk_add_f32 v[64:65], v[64:65], v[66:67]
	ds_bpermute_b32 v67, v191, v65
	ds_bpermute_b32 v66, v191, v64
	s_waitcnt lgkmcnt(0)
	v_pk_add_f32 v[64:65], v[64:65], v[66:67]
	ds_bpermute_b32 v67, v192, v65
	ds_bpermute_b32 v66, v192, v64
	s_waitcnt lgkmcnt(0)
	v_pk_add_f32 v[64:65], v[64:65], v[66:67]
	s_nop 0
	v_pk_fma_f32 v[64:65], v[64:65], s[82:83], v[116:117] op_sel_hi:[1,0,0]
	s_nop 0
	v_mul_f32_e32 v66, 0x4b800000, v65
	v_cmp_gt_f32_e64 s[6:7], s81, v65
	v_cmp_gt_f32_e64 s[4:5], s81, v64
	s_nop 0
	v_cndmask_b32_e64 v65, v65, v66, s[6:7]
	v_rsq_f32_e32 v65, v65
	s_nop 0
	v_mul_f32_e32 v66, 0x45800000, v65
	v_cndmask_b32_e64 v106, v65, v66, s[6:7]
	v_mul_f32_e32 v65, 0x4b800000, v64
	v_cndmask_b32_e64 v64, v64, v65, s[4:5]
	v_rsq_f32_e32 v64, v64
	v_pk_mul_f32 v[162:163], v[106:107], v[162:163] op_sel_hi:[0,1]
	v_mul_f32_e32 v65, 0x45800000, v64
	v_cndmask_b32_e64 v100, v64, v65, s[4:5]
	v_lshrrev_b32_e32 v64, 12, v72
	v_mad_u32_u24 v64, v64, s83, s83
	v_cndmask_b32_e64 v64, v64, 0, vcc
	v_mov_b32_e32 v65, v137
	v_lshl_add_u64 v[118:119], v[64:65], 2, s[84:85]
	v_lshl_add_u64 v[170:171], v[118:119], 0, s[2:3]
	global_load_dwordx4 v[64:67], v[78:79], off
	v_lshl_add_u64 v[68:69], v[170:171], 0, v[88:89]
	global_load_dwordx4 v[68:71], v[68:69], off
	s_movk_i32 s2, 0xd000
	v_add_co_u32_e32 v172, vcc, s2, v84
	v_pk_mul_f32 v[166:167], v[100:101], v[166:167] op_sel_hi:[0,1]
	s_nop 0
	v_addc_co_u32_e32 v173, vcc, -1, v85, vcc
	v_mov_b32_e32 v72, v75
	v_pk_mul_f32 v[72:73], v[98:99], v[72:73] op_sel_hi:[0,1]
	s_mov_b64 s[2:3], 0x3000
	s_waitcnt vmcnt(1)
	v_pk_mul_f32 v[146:147], v[146:147], v[64:65]
	v_pk_mul_f32 v[148:149], v[148:149], v[66:67]
	s_waitcnt vmcnt(0)
	v_pk_fma_f32 v[40:41], v[68:69], v[146:147], v[40:41]
	v_pk_fma_f32 v[42:43], v[70:71], v[148:149], v[42:43]
	v_pk_mul_f32 v[148:149], v[40:41], v[40:41]
	v_pk_mul_f32 v[146:147], v[42:43], v[42:43]
	v_pk_mul_f32 v[150:151], v[150:151], v[64:65]
	v_pk_mov_b32 v[194:195], v[148:149], v[146:147] op_sel:[1,0]
	v_mov_b32_e32 v149, v147
	v_pk_add_f32 v[146:147], v[194:195], v[148:149]
	v_pk_mul_f32 v[148:149], v[74:75], v[152:153] op_sel_hi:[0,1]
	v_pk_mul_f32 v[148:149], v[148:149], v[66:67]
	v_pk_fma_f32 v[44:45], v[68:69], v[150:151], v[44:45]
	v_pk_fma_f32 v[46:47], v[70:71], v[148:149], v[46:47]
	v_pk_mul_f32 v[152:153], v[44:45], v[44:45]
	v_pk_mul_f32 v[150:151], v[46:47], v[46:47]
	v_pk_mul_f32 v[162:163], v[64:65], v[162:163]
	v_pk_mov_b32 v[194:195], v[152:153], v[150:151] op_sel:[1,0]
	v_mov_b32_e32 v153, v151
	v_pk_add_f32 v[150:151], v[194:195], v[152:153]
	v_pk_mul_f32 v[152:153], v[106:107], v[164:165] op_sel_hi:[0,1]
	v_pk_mul_f32 v[152:153], v[66:67], v[152:153]
	v_pk_fma_f32 v[52:53], v[68:69], v[162:163], v[52:53]
	v_pk_fma_f32 v[54:55], v[70:71], v[152:153], v[54:55]
	v_pk_mul_f32 v[162:163], v[52:53], v[52:53]
	v_pk_mul_f32 v[152:153], v[54:55], v[54:55]
	v_add_co_u32_e32 v148, vcc, s80, v84
	v_pk_mov_b32 v[194:195], v[162:163], v[152:153] op_sel:[1,0]
	v_mov_b32_e32 v163, v153
	v_pk_add_f32 v[152:153], v[194:195], v[162:163]
	v_pk_mul_f32 v[162:163], v[100:101], v[168:169] op_sel_hi:[0,1]
	v_addc_co_u32_e32 v149, vcc, -1, v85, vcc
	v_pk_mul_f32 v[64:65], v[64:65], v[166:167]
	v_pk_mul_f32 v[66:67], v[66:67], v[162:163]
	v_add_co_u32_e32 v164, vcc, s33, v84
	v_pk_fma_f32 v[58:59], v[70:71], v[66:67], v[58:59]
	v_pk_fma_f32 v[56:57], v[68:69], v[64:65], v[56:57]
	v_addc_co_u32_e32 v165, vcc, -1, v85, vcc
	v_pk_mul_f32 v[64:65], v[58:59], v[58:59]
	v_pk_mul_f32 v[66:67], v[56:57], v[56:57]
	global_store_dwordx4 v[172:173], v[40:43], off offset:-3072 nt
	global_store_dwordx4 v[148:149], v[44:47], off offset:-3072 nt
	global_store_dwordx4 v[164:165], v[52:55], off offset:-3072 nt
	global_store_dwordx4 v[84:85], v[56:59], off offset:-3072 nt
	v_pk_mov_b32 v[68:69], v[66:67], v[64:65] op_sel:[1,0]
	v_mov_b32_e32 v67, v65
	v_pk_add_f32 v[162:163], v[68:69], v[66:67]
	global_load_dwordx4 v[64:67], v[78:79], off offset:1024
	v_lshl_add_u64 v[68:69], v[170:171], 0, v[90:91]
	global_load_dwordx4 v[68:71], v[68:69], off
	v_mov_b32_e32 v166, v130
	v_mov_b32_e32 v167, v128
	v_mov_b32_e32 v128, v131
	v_pk_mul_f32 v[166:167], v[98:99], v[166:167] op_sel_hi:[0,1]
	v_pk_mul_f32 v[128:129], v[98:99], v[128:129] op_sel_hi:[0,1]
	s_waitcnt vmcnt(1)
	v_pk_mul_f32 v[128:129], v[128:129], v[66:67]
	v_pk_mul_f32 v[130:131], v[166:167], v[64:65]
	s_waitcnt vmcnt(0)
	v_pk_fma_f32 v[30:31], v[70:71], v[128:129], v[30:31]
	v_pk_fma_f32 v[28:29], v[68:69], v[130:131], v[28:29]
	v_pk_mul_f32 v[130:131], v[30:31], v[30:31]
	v_pk_mul_f32 v[128:129], v[28:29], v[28:29]
	global_store_dwordx4 v[172:173], v[28:31], off offset:-2048 nt
	v_pk_mov_b32 v[166:167], v[128:129], v[130:131] op_sel:[1,0]
	v_mov_b32_e32 v129, v131
	v_mov_b32_e32 v130, v134
	v_mov_b32_e32 v131, v132
	v_mov_b32_e32 v132, v135
	v_pk_mul_f32 v[130:131], v[74:75], v[130:131] op_sel_hi:[0,1]
	v_pk_mul_f32 v[132:133], v[74:75], v[132:133] op_sel_hi:[0,1]
	v_pk_mul_f32 v[132:133], v[132:133], v[66:67]
	v_pk_mul_f32 v[130:131], v[130:131], v[64:65]
	v_pk_fma_f32 v[34:35], v[70:71], v[132:133], v[34:35]
	v_pk_fma_f32 v[32:33], v[68:69], v[130:131], v[32:33]
	v_pk_mul_f32 v[132:133], v[34:35], v[34:35]
	v_pk_mul_f32 v[130:131], v[32:33], v[32:33]
	global_store_dwordx4 v[148:149], v[32:35], off offset:-2048 nt
	v_pk_mov_b32 v[134:135], v[130:131], v[132:133] op_sel:[1,0]
	v_mov_b32_e32 v131, v133
	v_mov_b32_e32 v132, v156
	v_mov_b32_e32 v133, v154
	v_mov_b32_e32 v154, v157
	v_pk_add_f32 v[130:131], v[134:135], v[130:131]
	v_pk_mul_f32 v[132:133], v[106:107], v[132:133] op_sel_hi:[0,1]
	v_pk_mul_f32 v[134:135], v[106:107], v[154:155] op_sel_hi:[0,1]
	v_pk_mul_f32 v[134:135], v[134:135], v[66:67]
	v_pk_mul_f32 v[132:133], v[132:133], v[64:65]
	v_pk_fma_f32 v[38:39], v[70:71], v[134:135], v[38:39]
	v_pk_fma_f32 v[36:37], v[68:69], v[132:133], v[36:37]
	v_pk_mul_f32 v[134:135], v[38:39], v[38:39]
	v_pk_mul_f32 v[132:133], v[36:37], v[36:37]
	global_store_dwordx4 v[164:165], v[36:39], off offset:-2048 nt
	v_pk_mov_b32 v[154:155], v[132:133], v[134:135] op_sel:[1,0]
	v_mov_b32_e32 v133, v135
	v_mov_b32_e32 v134, v160
	v_mov_b32_e32 v135, v158
	v_mov_b32_e32 v158, v161
	v_pk_add_f32 v[132:133], v[154:155], v[132:133]
	v_pk_mul_f32 v[134:135], v[100:101], v[134:135] op_sel_hi:[0,1]
	v_pk_mul_f32 v[154:155], v[100:101], v[158:159] op_sel_hi:[0,1]
	v_pk_mul_f32 v[66:67], v[66:67], v[154:155]
	v_pk_mul_f32 v[64:65], v[64:65], v[134:135]
	v_pk_fma_f32 v[70:71], v[70:71], v[66:67], v[62:63]
	v_pk_fma_f32 v[68:69], v[68:69], v[64:65], v[60:61]
	v_pk_mul_f32 v[62:63], v[70:71], v[70:71]
	v_pk_mul_f32 v[60:61], v[68:69], v[68:69]
	global_store_dwordx4 v[84:85], v[68:71], off offset:-2048 nt
	v_pk_mov_b32 v[64:65], v[60:61], v[62:63] op_sel:[1,0]
	v_mov_b32_e32 v61, v63
	v_pk_add_f32 v[134:135], v[64:65], v[60:61]
	global_load_dwordx4 v[154:157], v[78:79], off offset:2048
	v_lshl_add_u64 v[60:61], v[170:171], 0, v[92:93]
	global_load_dwordx4 v[158:161], v[60:61], off
	v_pk_mul_f32 v[60:61], v[98:99], v[120:121] op_sel_hi:[0,1]
	v_pk_mul_f32 v[62:63], v[98:99], v[122:123] op_sel_hi:[0,1]
	v_pk_add_f32 v[128:129], v[166:167], v[128:129]
	s_waitcnt vmcnt(1)
	v_pk_mul_f32 v[62:63], v[62:63], v[156:157]
	v_pk_mul_f32 v[60:61], v[60:61], v[154:155]
	s_waitcnt vmcnt(0)
	v_pk_fma_f32 v[66:67], v[160:161], v[62:63], v[14:15]
	v_pk_fma_f32 v[64:65], v[158:159], v[60:61], v[12:13]
	v_pk_mul_f32 v[12:13], v[74:75], v[124:125] op_sel_hi:[0,1]
	v_pk_mul_f32 v[14:15], v[74:75], v[126:127] op_sel_hi:[0,1]
	v_pk_mul_f32 v[14:15], v[14:15], v[156:157]
	v_pk_mul_f32 v[12:13], v[12:13], v[154:155]
	v_pk_fma_f32 v[62:63], v[160:161], v[14:15], v[18:19]
	v_pk_fma_f32 v[60:61], v[158:159], v[12:13], v[16:17]
	v_pk_mul_f32 v[12:13], v[106:107], v[138:139] op_sel_hi:[0,1]
	v_pk_mul_f32 v[14:15], v[106:107], v[140:141] op_sel_hi:[0,1]
	v_pk_mul_f32 v[14:15], v[14:15], v[156:157]
	v_pk_mul_f32 v[12:13], v[12:13], v[154:155]
	v_pk_fma_f32 v[18:19], v[160:161], v[14:15], v[26:27]
	v_pk_fma_f32 v[16:17], v[158:159], v[12:13], v[24:25]
	v_pk_mul_f32 v[12:13], v[100:101], v[142:143] op_sel_hi:[0,1]
	v_pk_mul_f32 v[14:15], v[100:101], v[144:145] op_sel_hi:[0,1]
	v_pk_mul_f32 v[14:15], v[14:15], v[156:157]
	v_pk_mul_f32 v[12:13], v[12:13], v[154:155]
	v_pk_fma_f32 v[14:15], v[160:161], v[14:15], v[50:51]
	v_pk_fma_f32 v[12:13], v[158:159], v[12:13], v[48:49]
	global_store_dwordx4 v[172:173], v[64:67], off offset:-1024 nt
	global_store_dwordx4 v[148:149], v[60:63], off offset:-1024 nt
	global_store_dwordx4 v[164:165], v[16:19], off offset:-1024 nt
	global_store_dwordx4 v[84:85], v[12:15], off offset:-1024 nt
	global_load_dwordx4 v[24:27], v[78:79], off offset:3072
	v_lshl_add_u64 v[48:49], v[170:171], 0, v[94:95]
	global_load_dwordx4 v[48:51], v[48:49], off
	s_waitcnt vmcnt(1)
	v_pk_mul_f32 v[72:73], v[72:73], v[24:25]
	v_pk_mul_f32 v[96:97], v[96:97], v[26:27]
	s_waitcnt vmcnt(0)
	v_pk_fma_f32 v[0:1], v[48:49], v[72:73], v[0:1]
	v_pk_fma_f32 v[2:3], v[50:51], v[96:97], v[2:3]
	v_mul_f32_e32 v75, v0, v0
	v_mul_f32_e32 v77, v1, v1
	v_pk_add_f32 v[72:73], v[146:147], v[146:147] op_sel:[0,1] op_sel_hi:[1,0]
	v_pk_add_f32 v[96:97], v[128:129], v[128:129] op_sel:[0,1] op_sel_hi:[1,0]
	v_mov_b32_e32 v73, v75
	v_mov_b32_e32 v97, v77
	v_pk_add_f32 v[72:73], v[72:73], v[96:97]
	v_mul_f32_e32 v96, v65, v65
	v_mul_f32_e32 v98, v2, v2
	v_pk_fma_f32 v[96:97], v[64:65], v[64:65], v[96:97] op_sel_hi:[1,1,0]
	v_mul_f32_e32 v104, v3, v3
	v_mov_b32_e32 v97, v98
	v_mul_f32_e32 v98, v67, v67
	v_pk_fma_f32 v[120:121], v[66:67], v[66:67], v[98:99] op_sel_hi:[1,1,0]
	v_mov_b32_e32 v98, v101
	v_mov_b32_e32 v121, v104
	v_pk_add_f32 v[96:97], v[96:97], v[120:121]
	v_mov_b32_e32 v104, v107
	v_pk_add_f32 v[72:73], v[72:73], v[96:97]
	v_pk_mul_f32 v[96:97], v[74:75], v[102:103] op_sel_hi:[0,1]
	v_pk_mul_f32 v[74:75], v[74:75], v[98:99] op_sel_hi:[0,1]
	v_pk_mul_f32 v[74:75], v[74:75], v[24:25]
	v_pk_mul_f32 v[96:97], v[96:97], v[26:27]
	v_pk_fma_f32 v[4:5], v[48:49], v[74:75], v[4:5]
	v_pk_fma_f32 v[6:7], v[50:51], v[96:97], v[6:7]
	v_mul_f32_e32 v77, v4, v4
	v_mul_f32_e32 v98, v5, v5
	v_pk_add_f32 v[74:75], v[150:151], v[150:151] op_sel:[0,1] op_sel_hi:[1,0]
	v_pk_add_f32 v[96:97], v[130:131], v[130:131] op_sel:[0,1] op_sel_hi:[1,0]
	v_mov_b32_e32 v75, v77
	v_mov_b32_e32 v97, v98
	v_pk_add_f32 v[74:75], v[74:75], v[96:97]
	v_mul_f32_e32 v96, v61, v61
	v_mul_f32_e32 v99, v6, v6
	v_pk_fma_f32 v[96:97], v[60:61], v[60:61], v[96:97] op_sel_hi:[1,1,0]
	v_mul_f32_e32 v98, v63, v63
	v_mul_f32_e32 v101, v7, v7
	v_mov_b32_e32 v97, v99
	v_pk_fma_f32 v[98:99], v[62:63], v[62:63], v[98:99] op_sel_hi:[1,1,0]
	global_store_dwordx4 v[148:149], v[0:3], off offset:-4096 nt
	v_mov_b32_e32 v99, v101
	v_pk_add_f32 v[96:97], v[96:97], v[98:99]
	v_pk_mul_f32 v[98:99], v[106:107], v[104:105] op_sel_hi:[0,1]
	v_pk_add_f32 v[74:75], v[74:75], v[96:97]
	v_pk_mul_f32 v[96:97], v[106:107], v[108:109] op_sel_hi:[0,1]
	v_pk_mul_f32 v[98:99], v[98:99], v[24:25]
	v_pk_mul_f32 v[96:97], v[96:97], v[26:27]
	v_pk_fma_f32 v[8:9], v[48:49], v[98:99], v[8:9]
	v_pk_fma_f32 v[10:11], v[50:51], v[96:97], v[10:11]
	v_mul_f32_e32 v77, v8, v8
	v_mul_f32_e32 v101, v9, v9
	v_pk_add_f32 v[96:97], v[152:153], v[152:153] op_sel:[0,1] op_sel_hi:[1,0]
	v_pk_add_f32 v[98:99], v[132:133], v[132:133] op_sel:[0,1] op_sel_hi:[1,0]
	v_mov_b32_e32 v97, v77
	v_mov_b32_e32 v99, v101
	v_pk_add_f32 v[96:97], v[96:97], v[98:99]
	v_mul_f32_e32 v98, v17, v17
	v_mul_f32_e32 v102, v10, v10
	v_pk_fma_f32 v[98:99], v[16:17], v[16:17], v[98:99] op_sel_hi:[1,1,0]
	v_mul_f32_e32 v104, v11, v11
	v_mov_b32_e32 v99, v102
	v_mul_f32_e32 v102, v19, v19
	v_pk_fma_f32 v[102:103], v[18:19], v[18:19], v[102:103] op_sel_hi:[1,1,0]
	global_store_dwordx4 v[148:149], v[4:7], off nt
	v_mov_b32_e32 v103, v104
	v_pk_add_f32 v[98:99], v[98:99], v[102:103]
	global_store_dwordx4 v[84:85], v[8:11], off offset:-4096 nt
	v_pk_add_f32 v[98:99], v[96:97], v[98:99]
	v_pk_mul_f32 v[96:97], v[100:101], v[114:115] op_sel_hi:[0,1]
	v_pk_mul_f32 v[100:101], v[100:101], v[110:111] op_sel_hi:[0,1]
	v_pk_mul_f32 v[24:25], v[100:101], v[24:25]
	v_pk_mul_f32 v[26:27], v[96:97], v[26:27]
	v_pk_fma_f32 v[20:21], v[48:49], v[24:25], v[20:21]
	v_pk_fma_f32 v[22:23], v[50:51], v[26:27], v[22:23]
	v_mul_f32_e32 v26, v20, v20
	v_pk_add_f32 v[24:25], v[162:163], v[162:163] op_sel:[0,1] op_sel_hi:[1,0]
	v_mul_f32_e32 v48, v21, v21
	v_mov_b32_e32 v25, v26
	v_pk_add_f32 v[26:27], v[134:135], v[134:135] op_sel:[0,1] op_sel_hi:[1,0]
	v_mul_f32_e32 v49, v22, v22
	v_mov_b32_e32 v27, v48
	v_pk_add_f32 v[24:25], v[24:25], v[26:27]
	v_mul_f32_e32 v26, v13, v13
	v_pk_fma_f32 v[26:27], v[12:13], v[12:13], v[26:27] op_sel_hi:[1,1,0]
	v_mul_f32_e32 v48, v15, v15
	v_mul_f32_e32 v50, v23, v23
	v_mov_b32_e32 v27, v49
	v_pk_fma_f32 v[48:49], v[14:15], v[14:15], v[48:49] op_sel_hi:[1,1,0]
	global_store_dwordx4 v[84:85], v[20:23], off nt
	v_mov_b32_e32 v49, v50
	v_pk_add_f32 v[26:27], v[26:27], v[48:49]
	v_lshl_add_u64 v[104:105], v[118:119], 0, s[2:3]
	v_pk_add_f32 v[24:25], v[24:25], v[26:27]
	v_mov_b32_e32 v26, v74
	v_mov_b32_e32 v27, v72
	v_mov_b32_e32 v72, v75
	v_pk_add_f32 v[26:27], v[26:27], v[72:73]
	ds_bpermute_b32 v49, v187, v27
	ds_bpermute_b32 v48, v187, v26
	s_movk_i32 s2, 0x5fff
	v_lshl_add_u64 v[84:85], v[84:85], 0, s[72:73]
	s_waitcnt lgkmcnt(0)
	v_pk_add_f32 v[26:27], v[26:27], v[48:49]
	ds_bpermute_b32 v49, v188, v27
	ds_bpermute_b32 v48, v188, v26
	s_waitcnt lgkmcnt(0)
	v_pk_add_f32 v[26:27], v[26:27], v[48:49]
	ds_bpermute_b32 v49, v189, v27
	ds_bpermute_b32 v48, v189, v26
	s_waitcnt lgkmcnt(0)
	v_pk_add_f32 v[26:27], v[26:27], v[48:49]
	ds_bpermute_b32 v49, v190, v27
	ds_bpermute_b32 v48, v190, v26
	s_waitcnt lgkmcnt(0)
	v_pk_add_f32 v[26:27], v[26:27], v[48:49]
	ds_bpermute_b32 v49, v191, v27
	ds_bpermute_b32 v48, v191, v26
	s_waitcnt lgkmcnt(0)
	v_pk_add_f32 v[26:27], v[26:27], v[48:49]
	ds_bpermute_b32 v49, v192, v27
	ds_bpermute_b32 v48, v192, v26
	s_waitcnt lgkmcnt(0)
	v_pk_add_f32 v[26:27], v[26:27], v[48:49]
	s_nop 0
	v_pk_fma_f32 v[26:27], v[26:27], s[82:83], v[116:117] op_sel_hi:[1,0,0]
	s_nop 0
	v_mul_f32_e32 v48, 0x4b800000, v27
	v_cmp_gt_f32_e64 s[4:5], s81, v27
	v_cmp_gt_f32_e32 vcc, s81, v26
	s_nop 0
	v_cndmask_b32_e64 v27, v27, v48, s[4:5]
	v_rsq_f32_e32 v27, v27
	s_nop 0
	v_mul_f32_e32 v48, 0x45800000, v27
	v_cndmask_b32_e64 v100, v27, v48, s[4:5]
	v_mul_f32_e32 v27, 0x4b800000, v26
	v_cndmask_b32_e32 v26, v26, v27, vcc
	v_rsq_f32_e32 v26, v26
	v_lshl_add_u64 v[48:49], v[104:105], 0, v[88:89]
	global_load_dwordx4 v[48:51], v[48:49], off
	v_pk_mul_f32 v[42:43], v[42:43], v[100:101] op_sel_hi:[1,0]
	v_mul_f32_e32 v27, 0x45800000, v26
	v_cndmask_b32_e32 v96, v26, v27, vcc
	v_mov_b32_e32 v26, v24
	v_mov_b32_e32 v27, v98
	v_mov_b32_e32 v98, v25
	v_pk_add_f32 v[24:25], v[26:27], v[98:99]
	ds_bpermute_b32 v27, v187, v25
	ds_bpermute_b32 v26, v187, v24
	v_pk_mul_f32 v[40:41], v[40:41], v[100:101] op_sel_hi:[1,0]
	v_pk_mul_f32 v[44:45], v[44:45], v[96:97] op_sel_hi:[1,0]
	v_pk_mul_f32 v[30:31], v[30:31], v[100:101] op_sel_hi:[1,0]
	v_pk_mul_f32 v[28:29], v[28:29], v[100:101] op_sel_hi:[1,0]
	s_waitcnt lgkmcnt(0)
	v_pk_add_f32 v[24:25], v[24:25], v[26:27]
	ds_bpermute_b32 v27, v188, v25
	ds_bpermute_b32 v26, v188, v24
	v_pk_mul_f32 v[2:3], v[2:3], v[100:101] op_sel_hi:[1,0]
	v_pk_mul_f32 v[0:1], v[0:1], v[100:101] op_sel_hi:[1,0]
	s_waitcnt lgkmcnt(0)
	v_pk_add_f32 v[24:25], v[24:25], v[26:27]
	ds_bpermute_b32 v27, v189, v25
	ds_bpermute_b32 v26, v189, v24
	s_waitcnt lgkmcnt(0)
	v_pk_add_f32 v[24:25], v[24:25], v[26:27]
	ds_bpermute_b32 v27, v190, v25
	ds_bpermute_b32 v26, v190, v24
	s_waitcnt lgkmcnt(0)
	v_pk_add_f32 v[24:25], v[24:25], v[26:27]
	ds_bpermute_b32 v27, v191, v25
	ds_bpermute_b32 v26, v191, v24
	s_waitcnt lgkmcnt(0)
	v_pk_add_f32 v[24:25], v[24:25], v[26:27]
	ds_bpermute_b32 v27, v192, v25
	ds_bpermute_b32 v26, v192, v24
	s_waitcnt lgkmcnt(0)
	v_pk_add_f32 v[24:25], v[24:25], v[26:27]
	s_nop 0
	v_pk_fma_f32 v[24:25], v[24:25], s[82:83], v[116:117] op_sel_hi:[1,0,0]
	s_nop 0
	v_mul_f32_e32 v26, 0x4b800000, v25
	v_cmp_gt_f32_e64 s[4:5], s81, v25
	v_cmp_gt_f32_e32 vcc, s81, v24
	s_nop 0
	v_cndmask_b32_e64 v25, v25, v26, s[4:5]
	v_rsq_f32_e32 v25, v25
	s_nop 0
	v_mul_f32_e32 v26, 0x45800000, v25
	v_cndmask_b32_e64 v102, v25, v26, s[4:5]
	v_mul_f32_e32 v25, 0x4b800000, v24
	v_cndmask_b32_e32 v24, v24, v25, vcc
	v_rsq_f32_e32 v24, v24
	s_mov_b64 s[4:5], 0x4000
	v_lshl_add_u64 v[106:107], v[118:119], 0, s[4:5]
	v_lshl_add_u64 v[72:73], v[106:107], 0, v[88:89]
	v_mul_f32_e32 v25, 0x45800000, v24
	v_cndmask_b32_e32 v98, v24, v25, vcc
	global_load_dwordx4 v[24:27], v[80:81], off
	v_pk_mul_f32 v[16:17], v[16:17], v[102:103] op_sel_hi:[1,0]
	global_load_dwordx4 v[72:75], v[72:73], off
	v_pk_mul_f32 v[12:13], v[12:13], v[98:99] op_sel_hi:[1,0]
	v_pk_mul_f32 v[18:19], v[18:19], v[102:103] op_sel_hi:[1,0]
	v_pk_mul_f32 v[14:15], v[14:15], v[98:99] op_sel_hi:[1,0]
	s_waitcnt vmcnt(1)
	v_pk_mul_f32 v[40:41], v[40:41], v[24:25]
	v_pk_mul_f32 v[42:43], v[42:43], v[26:27]
	s_waitcnt vmcnt(0)
	v_pk_add_f32 v[74:75], v[74:75], 1.0 op_sel_hi:[1,0]
	v_pk_add_f32 v[72:73], v[72:73], 1.0 op_sel_hi:[1,0]
	v_pk_fma_f32 v[42:43], v[42:43], v[74:75], v[50:51]
	v_pk_fma_f32 v[40:41], v[40:41], v[72:73], v[48:49]
	v_pk_mul_f32 v[44:45], v[44:45], v[24:25]
	v_cvt_pk_bf16_f32 v108, v40, v41
	v_cvt_pk_bf16_f32 v109, v42, v43
	v_add_co_u32_e32 v40, vcc, s33, v86
	v_pk_mul_f32 v[42:43], v[46:47], v[96:97] op_sel_hi:[1,0]
	s_nop 0
	v_addc_co_u32_e32 v41, vcc, -1, v87, vcc
	v_pk_mul_f32 v[42:43], v[42:43], v[26:27]
	v_pk_fma_f32 v[44:45], v[44:45], v[72:73], v[48:49]
	global_store_dwordx2 v[40:41], v[108:109], off offset:-3584
	v_pk_fma_f32 v[42:43], v[42:43], v[74:75], v[50:51]
	v_cvt_pk_bf16_f32 v44, v44, v45
	v_lshl_add_u64 v[46:47], v[106:107], 0, v[90:91]
	v_cvt_pk_bf16_f32 v45, v42, v43
	global_store_dwordx2 v[40:41], v[44:45], off offset:-1536
	v_pk_mul_f32 v[44:45], v[52:53], v[102:103] op_sel_hi:[1,0]
	v_pk_mul_f32 v[42:43], v[54:55], v[102:103] op_sel_hi:[1,0]
	v_pk_mul_f32 v[44:45], v[24:25], v[44:45]
	v_pk_mul_f32 v[42:43], v[26:27], v[42:43]
	v_pk_fma_f32 v[44:45], v[72:73], v[44:45], v[48:49]
	v_pk_fma_f32 v[42:43], v[74:75], v[42:43], v[50:51]
	v_cvt_pk_bf16_f32 v44, v44, v45
	v_cmp_lt_i32_e32 vcc, s2, v76
	v_cvt_pk_bf16_f32 v45, v42, v43
	global_store_dwordx2 v[86:87], v[44:45], off offset:-3584
	v_pk_mul_f32 v[44:45], v[56:57], v[98:99] op_sel_hi:[1,0]
	v_pk_mul_f32 v[42:43], v[58:59], v[98:99] op_sel_hi:[1,0]
	v_pk_mul_f32 v[24:25], v[24:25], v[44:45]
	v_pk_mul_f32 v[26:27], v[26:27], v[42:43]
	v_pk_fma_f32 v[24:25], v[72:73], v[24:25], v[48:49]
	v_pk_fma_f32 v[26:27], v[74:75], v[26:27], v[50:51]
	v_cvt_pk_bf16_f32 v24, v24, v25
	v_lshl_add_u64 v[42:43], v[104:105], 0, v[90:91]
	v_cvt_pk_bf16_f32 v25, v26, v27
	global_store_dwordx2 v[86:87], v[24:25], off offset:-1536
	global_load_dwordx4 v[24:27], v[80:81], off offset:1024
	s_or_b64 s[10:11], vcc, s[10:11]
	global_load_dwordx4 v[46:49], v[46:47], off
	s_waitcnt vmcnt(1)
	v_pk_mul_f32 v[28:29], v[28:29], v[24:25]
	global_load_dwordx4 v[42:45], v[42:43], off
	s_waitcnt vmcnt(1)
	v_pk_add_f32 v[48:49], v[48:49], 1.0 op_sel_hi:[1,0]
	v_pk_add_f32 v[46:47], v[46:47], 1.0 op_sel_hi:[1,0]
	v_pk_mul_f32 v[30:31], v[30:31], v[26:27]
	s_waitcnt vmcnt(0)
	v_pk_fma_f32 v[28:29], v[28:29], v[46:47], v[42:43]
	v_pk_fma_f32 v[30:31], v[30:31], v[48:49], v[44:45]
	v_cvt_pk_bf16_f32 v28, v28, v29
	s_nop 0
	v_cvt_pk_bf16_f32 v29, v30, v31
	v_pk_mul_f32 v[30:31], v[32:33], v[96:97] op_sel_hi:[1,0]
	global_store_dwordx2 v[40:41], v[28:29], off offset:-3072
	v_pk_mul_f32 v[28:29], v[34:35], v[96:97] op_sel_hi:[1,0]
	v_pk_mul_f32 v[30:31], v[30:31], v[24:25]
	v_pk_mul_f32 v[28:29], v[28:29], v[26:27]
	v_pk_fma_f32 v[30:31], v[30:31], v[46:47], v[42:43]
	v_pk_fma_f32 v[28:29], v[28:29], v[48:49], v[44:45]
	v_cvt_pk_bf16_f32 v30, v30, v31
	v_lshl_add_u64 v[32:33], v[106:107], 0, v[92:93]
	v_cvt_pk_bf16_f32 v31, v28, v29
	global_store_dwordx2 v[40:41], v[30:31], off offset:-1024
	v_pk_mul_f32 v[30:31], v[36:37], v[102:103] op_sel_hi:[1,0]
	v_pk_mul_f32 v[28:29], v[38:39], v[102:103] op_sel_hi:[1,0]
	v_pk_mul_f32 v[30:31], v[30:31], v[24:25]
	v_pk_mul_f32 v[28:29], v[28:29], v[26:27]
	v_pk_fma_f32 v[30:31], v[30:31], v[46:47], v[42:43]
	v_pk_fma_f32 v[28:29], v[28:29], v[48:49], v[44:45]
	v_cvt_pk_bf16_f32 v30, v30, v31
	v_pk_mul_f32 v[38:39], v[64:65], v[100:101] op_sel_hi:[1,0]
	v_cvt_pk_bf16_f32 v31, v28, v29
	global_store_dwordx2 v[86:87], v[30:31], off offset:-3072
	v_pk_mul_f32 v[30:31], v[68:69], v[98:99] op_sel_hi:[1,0]
	v_pk_mul_f32 v[28:29], v[70:71], v[98:99] op_sel_hi:[1,0]
	v_pk_mul_f32 v[24:25], v[30:31], v[24:25]
	v_pk_mul_f32 v[26:27], v[28:29], v[26:27]
	v_pk_fma_f32 v[24:25], v[24:25], v[46:47], v[42:43]
	v_pk_fma_f32 v[26:27], v[26:27], v[48:49], v[44:45]
	v_cvt_pk_bf16_f32 v24, v24, v25
	v_lshl_add_u64 v[28:29], v[104:105], 0, v[92:93]
	v_cvt_pk_bf16_f32 v25, v26, v27
	global_store_dwordx2 v[86:87], v[24:25], off offset:-1024
	global_load_dwordx4 v[24:27], v[80:81], off offset:2048
	v_pk_mul_f32 v[36:37], v[66:67], v[100:101] op_sel_hi:[1,0]
	global_load_dwordx4 v[32:35], v[32:33], off
	s_waitcnt vmcnt(1)
	v_pk_mul_f32 v[38:39], v[38:39], v[24:25]
	global_load_dwordx4 v[28:31], v[28:29], off
	s_waitcnt vmcnt(1)
	v_pk_add_f32 v[32:33], v[32:33], 1.0 op_sel_hi:[1,0]
	v_pk_add_f32 v[34:35], v[34:35], 1.0 op_sel_hi:[1,0]
	v_pk_mul_f32 v[36:37], v[36:37], v[26:27]
	v_pk_mul_f32 v[16:17], v[16:17], v[24:25]
	v_pk_mul_f32 v[12:13], v[12:13], v[24:25]
	v_pk_mul_f32 v[18:19], v[18:19], v[26:27]
	v_pk_mul_f32 v[14:15], v[14:15], v[26:27]
	s_waitcnt vmcnt(0)
	v_pk_fma_f32 v[38:39], v[38:39], v[32:33], v[28:29]
	v_pk_fma_f32 v[36:37], v[36:37], v[34:35], v[30:31]
	v_cvt_pk_bf16_f32 v38, v38, v39
	v_pk_fma_f32 v[16:17], v[16:17], v[32:33], v[28:29]
	v_cvt_pk_bf16_f32 v39, v36, v37
	global_store_dwordx2 v[40:41], v[38:39], off offset:-2560
	v_pk_mul_f32 v[38:39], v[60:61], v[96:97] op_sel_hi:[1,0]
	v_pk_mul_f32 v[36:37], v[62:63], v[96:97] op_sel_hi:[1,0]
	v_pk_mul_f32 v[38:39], v[38:39], v[24:25]
	v_pk_mul_f32 v[36:37], v[36:37], v[26:27]
	v_pk_fma_f32 v[38:39], v[38:39], v[32:33], v[28:29]
	v_pk_fma_f32 v[12:13], v[12:13], v[32:33], v[28:29]
	v_pk_fma_f32 v[36:37], v[36:37], v[34:35], v[30:31]
	v_cvt_pk_bf16_f32 v38, v38, v39
	v_pk_fma_f32 v[18:19], v[18:19], v[34:35], v[30:31]
	v_cvt_pk_bf16_f32 v39, v36, v37
	global_store_dwordx2 v[40:41], v[38:39], off offset:-512
	v_cvt_pk_bf16_f32 v16, v16, v17
	v_cvt_pk_bf16_f32 v17, v18, v19
	global_store_dwordx2 v[86:87], v[16:17], off offset:-2560
	v_pk_fma_f32 v[14:15], v[14:15], v[34:35], v[30:31]
	v_cvt_pk_bf16_f32 v12, v12, v13
	v_lshl_add_u64 v[24:25], v[106:107], 0, v[94:95]
	v_cvt_pk_bf16_f32 v13, v14, v15
	global_store_dwordx2 v[86:87], v[12:13], off offset:-512
	global_load_dwordx4 v[12:15], v[80:81], off offset:3072
	v_lshl_add_u64 v[16:17], v[104:105], 0, v[94:95]
	global_load_dwordx4 v[24:27], v[24:25], off
	s_waitcnt vmcnt(1)
	v_pk_mul_f32 v[0:1], v[0:1], v[12:13]
	global_load_dwordx4 v[16:19], v[16:17], off
	s_waitcnt vmcnt(1)
	v_pk_add_f32 v[26:27], v[26:27], 1.0 op_sel_hi:[1,0]
	v_pk_add_f32 v[24:25], v[24:25], 1.0 op_sel_hi:[1,0]
	v_pk_mul_f32 v[2:3], v[2:3], v[14:15]
	s_waitcnt vmcnt(0)
	v_pk_fma_f32 v[0:1], v[0:1], v[24:25], v[16:17]
	v_pk_fma_f32 v[2:3], v[2:3], v[26:27], v[18:19]
	v_cvt_pk_bf16_f32 v0, v0, v1
	s_nop 0
	v_cvt_pk_bf16_f32 v1, v2, v3
	v_pk_mul_f32 v[2:3], v[4:5], v[96:97] op_sel_hi:[1,0]
	global_store_dwordx2 v[40:41], v[0:1], off offset:-2048
	v_pk_mul_f32 v[0:1], v[6:7], v[96:97] op_sel_hi:[1,0]
	v_pk_mul_f32 v[2:3], v[2:3], v[12:13]
	v_pk_mul_f32 v[0:1], v[0:1], v[14:15]
	v_pk_fma_f32 v[2:3], v[2:3], v[24:25], v[16:17]
	v_pk_fma_f32 v[0:1], v[0:1], v[26:27], v[18:19]
	v_cvt_pk_bf16_f32 v2, v2, v3
	s_nop 0
	v_cvt_pk_bf16_f32 v3, v0, v1
	global_store_dwordx2 v[86:87], v[2:3], off offset:-4096
	v_pk_mul_f32 v[2:3], v[8:9], v[102:103] op_sel_hi:[1,0]
	v_pk_mul_f32 v[0:1], v[10:11], v[102:103] op_sel_hi:[1,0]
	v_pk_mul_f32 v[2:3], v[2:3], v[12:13]
	v_pk_mul_f32 v[0:1], v[0:1], v[14:15]
	v_pk_fma_f32 v[2:3], v[2:3], v[24:25], v[16:17]
	v_pk_fma_f32 v[0:1], v[0:1], v[26:27], v[18:19]
	v_cvt_pk_bf16_f32 v2, v2, v3
	s_nop 0
	v_cvt_pk_bf16_f32 v3, v0, v1
	global_store_dwordx2 v[86:87], v[2:3], off offset:-2048
	v_pk_mul_f32 v[2:3], v[20:21], v[98:99] op_sel_hi:[1,0]
	v_pk_mul_f32 v[0:1], v[22:23], v[98:99] op_sel_hi:[1,0]
	v_pk_mul_f32 v[2:3], v[2:3], v[12:13]
	v_pk_mul_f32 v[0:1], v[0:1], v[14:15]
	v_pk_fma_f32 v[2:3], v[2:3], v[24:25], v[16:17]
	v_pk_fma_f32 v[0:1], v[0:1], v[26:27], v[18:19]
	v_cvt_pk_bf16_f32 v2, v2, v3
	s_nop 0
	v_cvt_pk_bf16_f32 v3, v0, v1
	global_store_dwordx2 v[86:87], v[2:3], off
	v_lshl_add_u64 v[86:87], v[86:87], 0, s[76:77]
	s_andn2_b64 exec, exec, s[10:11]
	s_cbranch_execnz .LBB0_1534
